# adds F-epilogue weight loads hoisted above the half-align barrier and a rewritten phase-D fused norm hand-off (modulation vectors loaded once, 8 wave reductions interleaved)
# speedup vs baseline: 1.0092x; 1.0092x over previous
.LBB0_1125:
	v_readlane_b32 s3, v255, 8
	s_lshl_b32 s80, s3, 10
	s_lshl_b64 s[6:7], s[80:81], 2
	s_waitcnt vmcnt(32)
	v_lshl_add_u64 v[28:29], v[28:29], 0, s[6:7]
	v_readlane_b32 s6, v255, 19
	s_add_u32 s10, s18, 0xe000000
	v_readlane_b32 s7, v255, 20
	s_addc_u32 s11, s19, 0
	s_lshl_b64 s[6:7], s[6:7], 2
	s_add_u32 s3, s18, s6
	s_addc_u32 s5, s19, s7
	v_readlane_b32 s6, v254, 48
	s_cmp_gt_i32 s6, 31
	s_cselect_b32 s6, 0x6000, 0
	v_readlane_b32 s7, v254, 49
	s_add_u32 s6, s3, s6
	s_addc_u32 s7, s5, 0
	s_add_u32 s18, s6, 0x3000
	s_addc_u32 s19, s7, 0
	s_add_u32 s20, s6, 0x4000
	v_readfirstlane_b32 s28, v28
	v_readfirstlane_b32 s29, v29
	s_addc_u32 s21, s7, 0
	s_nop 3
	global_load_dwordx4 v[100:103], v18, s[28:29]
	global_load_dwordx4 v[116:119], v18, s[18:19]
	global_load_dwordx4 v[132:135], v18, s[20:21]
	global_load_dwordx4 v[104:107], v18, s[28:29] offset:1024
	global_load_dwordx4 v[120:123], v18, s[18:19] offset:1024
	global_load_dwordx4 v[136:139], v18, s[20:21] offset:1024
	global_load_dwordx4 v[108:111], v18, s[28:29] offset:2048
	global_load_dwordx4 v[124:127], v18, s[18:19] offset:2048
	global_load_dwordx4 v[140:143], v18, s[20:21] offset:2048
	global_load_dwordx4 v[112:115], v18, s[28:29] offset:3072
	global_load_dwordx4 v[128:131], v18, s[18:19] offset:3072
	global_load_dwordx4 v[144:147], v18, s[20:21] offset:3072
	v_add_u32_e32 v92, 0x400, v18
	v_add_u32_e32 v88, 0x800, v18
	v_lshl_add_u64 v[182:183], s[10:11], 0, v[0:1]
	s_waitcnt vmcnt(12)
	v_lshlrev_b32_e32 v166, 16, v84
	v_and_b32_e32 v167, 0xffff0000, v84
	v_lshlrev_b32_e32 v168, 16, v85
	v_and_b32_e32 v169, 0xffff0000, v85
	v_lshlrev_b32_e32 v170, 16, v82
	v_and_b32_e32 v171, 0xffff0000, v82
	v_lshlrev_b32_e32 v172, 16, v83
	v_and_b32_e32 v173, 0xffff0000, v83
	v_lshlrev_b32_e32 v174, 16, v80
	v_and_b32_e32 v175, 0xffff0000, v80
	v_lshlrev_b32_e32 v176, 16, v81
	v_and_b32_e32 v177, 0xffff0000, v81
	v_lshlrev_b32_e32 v178, 16, v38
	v_and_b32_e32 v179, 0xffff0000, v38
	v_lshlrev_b32_e32 v180, 16, v39
	v_and_b32_e32 v181, 0xffff0000, v39
	v_pk_mul_f32 v[186:187], v[166:167], v[166:167]
	v_pk_fma_f32 v[186:187], v[168:169], v[168:169], v[186:187]
	v_pk_fma_f32 v[186:187], v[170:171], v[170:171], v[186:187]
	v_pk_fma_f32 v[186:187], v[172:173], v[172:173], v[186:187]
	v_pk_fma_f32 v[186:187], v[174:175], v[174:175], v[186:187]
	v_pk_fma_f32 v[186:187], v[176:177], v[176:177], v[186:187]
	v_pk_fma_f32 v[186:187], v[178:179], v[178:179], v[186:187]
	v_pk_fma_f32 v[186:187], v[180:181], v[180:181], v[186:187]
	v_add_f32_e32 v150, v186, v187
	v_lshlrev_b32_e32 v166, 16, v78
	v_and_b32_e32 v167, 0xffff0000, v78
	v_lshlrev_b32_e32 v168, 16, v79
	v_and_b32_e32 v169, 0xffff0000, v79
	v_lshlrev_b32_e32 v170, 16, v76
	v_and_b32_e32 v171, 0xffff0000, v76
	v_lshlrev_b32_e32 v172, 16, v77
	v_and_b32_e32 v173, 0xffff0000, v77
	v_lshlrev_b32_e32 v174, 16, v74
	v_and_b32_e32 v175, 0xffff0000, v74
	v_lshlrev_b32_e32 v176, 16, v75
	v_and_b32_e32 v177, 0xffff0000, v75
	v_lshlrev_b32_e32 v178, 16, v72
	v_and_b32_e32 v179, 0xffff0000, v72
	v_lshlrev_b32_e32 v180, 16, v73
	v_and_b32_e32 v181, 0xffff0000, v73
	v_pk_mul_f32 v[186:187], v[166:167], v[166:167]
	v_pk_fma_f32 v[186:187], v[168:169], v[168:169], v[186:187]
	v_pk_fma_f32 v[186:187], v[170:171], v[170:171], v[186:187]
	v_pk_fma_f32 v[186:187], v[172:173], v[172:173], v[186:187]
	v_pk_fma_f32 v[186:187], v[174:175], v[174:175], v[186:187]
	v_pk_fma_f32 v[186:187], v[176:177], v[176:177], v[186:187]
	v_pk_fma_f32 v[186:187], v[178:179], v[178:179], v[186:187]
	v_pk_fma_f32 v[186:187], v[180:181], v[180:181], v[186:187]
	v_add_f32_e32 v152, v186, v187
	v_lshlrev_b32_e32 v166, 16, v70
	v_and_b32_e32 v167, 0xffff0000, v70
	v_lshlrev_b32_e32 v168, 16, v71
	v_and_b32_e32 v169, 0xffff0000, v71
	v_lshlrev_b32_e32 v170, 16, v68
	v_and_b32_e32 v171, 0xffff0000, v68
	v_lshlrev_b32_e32 v172, 16, v69
	v_and_b32_e32 v173, 0xffff0000, v69
	v_lshlrev_b32_e32 v174, 16, v66
	v_and_b32_e32 v175, 0xffff0000, v66
	v_lshlrev_b32_e32 v176, 16, v67
	v_and_b32_e32 v177, 0xffff0000, v67
	v_lshlrev_b32_e32 v178, 16, v64
	v_and_b32_e32 v179, 0xffff0000, v64
	v_lshlrev_b32_e32 v180, 16, v65
	v_and_b32_e32 v181, 0xffff0000, v65
	v_pk_mul_f32 v[186:187], v[166:167], v[166:167]
	v_pk_fma_f32 v[186:187], v[168:169], v[168:169], v[186:187]
	v_pk_fma_f32 v[186:187], v[170:171], v[170:171], v[186:187]
	v_pk_fma_f32 v[186:187], v[172:173], v[172:173], v[186:187]
	v_pk_fma_f32 v[186:187], v[174:175], v[174:175], v[186:187]
	v_pk_fma_f32 v[186:187], v[176:177], v[176:177], v[186:187]
	v_pk_fma_f32 v[186:187], v[178:179], v[178:179], v[186:187]
	v_pk_fma_f32 v[186:187], v[180:181], v[180:181], v[186:187]
	v_add_f32_e32 v154, v186, v187
	v_lshlrev_b32_e32 v166, 16, v62
	v_and_b32_e32 v167, 0xffff0000, v62
	v_lshlrev_b32_e32 v168, 16, v63
	v_and_b32_e32 v169, 0xffff0000, v63
	v_lshlrev_b32_e32 v170, 16, v60
	v_and_b32_e32 v171, 0xffff0000, v60
	v_lshlrev_b32_e32 v172, 16, v61
	v_and_b32_e32 v173, 0xffff0000, v61
	v_lshlrev_b32_e32 v174, 16, v58
	v_and_b32_e32 v175, 0xffff0000, v58
	v_lshlrev_b32_e32 v176, 16, v59
	v_and_b32_e32 v177, 0xffff0000, v59
	v_lshlrev_b32_e32 v178, 16, v56
	v_and_b32_e32 v179, 0xffff0000, v56
	v_lshlrev_b32_e32 v180, 16, v57
	v_and_b32_e32 v181, 0xffff0000, v57
	v_pk_mul_f32 v[186:187], v[166:167], v[166:167]
	v_pk_fma_f32 v[186:187], v[168:169], v[168:169], v[186:187]
	v_pk_fma_f32 v[186:187], v[170:171], v[170:171], v[186:187]
	v_pk_fma_f32 v[186:187], v[172:173], v[172:173], v[186:187]
	v_pk_fma_f32 v[186:187], v[174:175], v[174:175], v[186:187]
	v_pk_fma_f32 v[186:187], v[176:177], v[176:177], v[186:187]
	v_pk_fma_f32 v[186:187], v[178:179], v[178:179], v[186:187]
	v_pk_fma_f32 v[186:187], v[180:181], v[180:181], v[186:187]
	v_add_f32_e32 v156, v186, v187
	v_lshlrev_b32_e32 v166, 16, v54
	v_and_b32_e32 v167, 0xffff0000, v54
	v_lshlrev_b32_e32 v168, 16, v55
	v_and_b32_e32 v169, 0xffff0000, v55
	v_lshlrev_b32_e32 v170, 16, v52
	v_and_b32_e32 v171, 0xffff0000, v52
	v_lshlrev_b32_e32 v172, 16, v53
	v_and_b32_e32 v173, 0xffff0000, v53
	v_lshlrev_b32_e32 v174, 16, v50
	v_and_b32_e32 v175, 0xffff0000, v50
	v_lshlrev_b32_e32 v176, 16, v51
	v_and_b32_e32 v177, 0xffff0000, v51
	v_lshlrev_b32_e32 v178, 16, v48
	v_and_b32_e32 v179, 0xffff0000, v48
	v_lshlrev_b32_e32 v180, 16, v49
	v_and_b32_e32 v181, 0xffff0000, v49
	v_pk_mul_f32 v[186:187], v[166:167], v[166:167]
	v_pk_fma_f32 v[186:187], v[168:169], v[168:169], v[186:187]
	v_pk_fma_f32 v[186:187], v[170:171], v[170:171], v[186:187]
	v_pk_fma_f32 v[186:187], v[172:173], v[172:173], v[186:187]
	v_pk_fma_f32 v[186:187], v[174:175], v[174:175], v[186:187]
	v_pk_fma_f32 v[186:187], v[176:177], v[176:177], v[186:187]
	v_pk_fma_f32 v[186:187], v[178:179], v[178:179], v[186:187]
	v_pk_fma_f32 v[186:187], v[180:181], v[180:181], v[186:187]
	v_add_f32_e32 v158, v186, v187
	v_lshlrev_b32_e32 v166, 16, v46
	v_and_b32_e32 v167, 0xffff0000, v46
	v_lshlrev_b32_e32 v168, 16, v47
	v_and_b32_e32 v169, 0xffff0000, v47
	v_lshlrev_b32_e32 v170, 16, v44
	v_and_b32_e32 v171, 0xffff0000, v44
	v_lshlrev_b32_e32 v172, 16, v45
	v_and_b32_e32 v173, 0xffff0000, v45
	v_lshlrev_b32_e32 v174, 16, v42
	v_and_b32_e32 v175, 0xffff0000, v42
	v_lshlrev_b32_e32 v176, 16, v43
	v_and_b32_e32 v177, 0xffff0000, v43
	v_lshlrev_b32_e32 v178, 16, v40
	v_and_b32_e32 v179, 0xffff0000, v40
	v_lshlrev_b32_e32 v180, 16, v41
	v_and_b32_e32 v181, 0xffff0000, v41
	v_pk_mul_f32 v[186:187], v[166:167], v[166:167]
	v_pk_fma_f32 v[186:187], v[168:169], v[168:169], v[186:187]
	v_pk_fma_f32 v[186:187], v[170:171], v[170:171], v[186:187]
	v_pk_fma_f32 v[186:187], v[172:173], v[172:173], v[186:187]
	v_pk_fma_f32 v[186:187], v[174:175], v[174:175], v[186:187]
	v_pk_fma_f32 v[186:187], v[176:177], v[176:177], v[186:187]
	v_pk_fma_f32 v[186:187], v[178:179], v[178:179], v[186:187]
	v_pk_fma_f32 v[186:187], v[180:181], v[180:181], v[186:187]
	v_add_f32_e32 v160, v186, v187
	v_lshlrev_b32_e32 v166, 16, v36
	v_and_b32_e32 v167, 0xffff0000, v36
	v_lshlrev_b32_e32 v168, 16, v37
	v_and_b32_e32 v169, 0xffff0000, v37
	v_lshlrev_b32_e32 v170, 16, v34
	v_and_b32_e32 v171, 0xffff0000, v34
	v_lshlrev_b32_e32 v172, 16, v35
	v_and_b32_e32 v173, 0xffff0000, v35
	v_lshlrev_b32_e32 v174, 16, v32
	v_and_b32_e32 v175, 0xffff0000, v32
	v_lshlrev_b32_e32 v176, 16, v33
	v_and_b32_e32 v177, 0xffff0000, v33
	v_lshlrev_b32_e32 v178, 16, v30
	v_and_b32_e32 v179, 0xffff0000, v30
	v_lshlrev_b32_e32 v180, 16, v31
	v_and_b32_e32 v181, 0xffff0000, v31
	v_pk_mul_f32 v[186:187], v[166:167], v[166:167]
	v_pk_fma_f32 v[186:187], v[168:169], v[168:169], v[186:187]
	v_pk_fma_f32 v[186:187], v[170:171], v[170:171], v[186:187]
	v_pk_fma_f32 v[186:187], v[172:173], v[172:173], v[186:187]
	v_pk_fma_f32 v[186:187], v[174:175], v[174:175], v[186:187]
	v_pk_fma_f32 v[186:187], v[176:177], v[176:177], v[186:187]
	v_pk_fma_f32 v[186:187], v[178:179], v[178:179], v[186:187]
	v_pk_fma_f32 v[186:187], v[180:181], v[180:181], v[186:187]
	v_add_f32_e32 v162, v186, v187
	v_lshlrev_b32_e32 v166, 16, v26
	v_and_b32_e32 v167, 0xffff0000, v26
	v_lshlrev_b32_e32 v168, 16, v27
	v_and_b32_e32 v169, 0xffff0000, v27
	v_lshlrev_b32_e32 v170, 16, v24
	v_and_b32_e32 v171, 0xffff0000, v24
	v_lshlrev_b32_e32 v172, 16, v25
	v_and_b32_e32 v173, 0xffff0000, v25
	v_lshlrev_b32_e32 v174, 16, v22
	v_and_b32_e32 v175, 0xffff0000, v22
	v_lshlrev_b32_e32 v176, 16, v23
	v_and_b32_e32 v177, 0xffff0000, v23
	v_lshlrev_b32_e32 v178, 16, v20
	v_and_b32_e32 v179, 0xffff0000, v20
	v_lshlrev_b32_e32 v180, 16, v21
	v_and_b32_e32 v181, 0xffff0000, v21
	v_pk_mul_f32 v[186:187], v[166:167], v[166:167]
	v_pk_fma_f32 v[186:187], v[168:169], v[168:169], v[186:187]
	v_pk_fma_f32 v[186:187], v[170:171], v[170:171], v[186:187]
	v_pk_fma_f32 v[186:187], v[172:173], v[172:173], v[186:187]
	v_pk_fma_f32 v[186:187], v[174:175], v[174:175], v[186:187]
	v_pk_fma_f32 v[186:187], v[176:177], v[176:177], v[186:187]
	v_pk_fma_f32 v[186:187], v[178:179], v[178:179], v[186:187]
	v_pk_fma_f32 v[186:187], v[180:181], v[180:181], v[186:187]
	v_add_f32_e32 v164, v186, v187
	ds_bpermute_b32 v151, v227, v150
	ds_bpermute_b32 v153, v227, v152
	ds_bpermute_b32 v155, v227, v154
	ds_bpermute_b32 v157, v227, v156
	ds_bpermute_b32 v159, v227, v158
	ds_bpermute_b32 v161, v227, v160
	ds_bpermute_b32 v163, v227, v162
	ds_bpermute_b32 v165, v227, v164
	s_waitcnt lgkmcnt(0)
	v_add_f32_e32 v150, v150, v151
	v_add_f32_e32 v152, v152, v153
	v_add_f32_e32 v154, v154, v155
	v_add_f32_e32 v156, v156, v157
	v_add_f32_e32 v158, v158, v159
	v_add_f32_e32 v160, v160, v161
	v_add_f32_e32 v162, v162, v163
	v_add_f32_e32 v164, v164, v165
	ds_bpermute_b32 v151, v228, v150
	ds_bpermute_b32 v153, v228, v152
	ds_bpermute_b32 v155, v228, v154
	ds_bpermute_b32 v157, v228, v156
	ds_bpermute_b32 v159, v228, v158
	ds_bpermute_b32 v161, v228, v160
	ds_bpermute_b32 v163, v228, v162
	ds_bpermute_b32 v165, v228, v164
	s_waitcnt lgkmcnt(0)
	v_add_f32_e32 v150, v150, v151
	v_add_f32_e32 v152, v152, v153
	v_add_f32_e32 v154, v154, v155
	v_add_f32_e32 v156, v156, v157
	v_add_f32_e32 v158, v158, v159
	v_add_f32_e32 v160, v160, v161
	v_add_f32_e32 v162, v162, v163
	v_add_f32_e32 v164, v164, v165
	ds_bpermute_b32 v151, v229, v150
	ds_bpermute_b32 v153, v229, v152
	ds_bpermute_b32 v155, v229, v154
	ds_bpermute_b32 v157, v229, v156
	ds_bpermute_b32 v159, v229, v158
	ds_bpermute_b32 v161, v229, v160
	ds_bpermute_b32 v163, v229, v162
	ds_bpermute_b32 v165, v229, v164
	s_waitcnt lgkmcnt(0)
	v_add_f32_e32 v150, v150, v151
	v_add_f32_e32 v152, v152, v153
	v_add_f32_e32 v154, v154, v155
	v_add_f32_e32 v156, v156, v157
	v_add_f32_e32 v158, v158, v159
	v_add_f32_e32 v160, v160, v161
	v_add_f32_e32 v162, v162, v163
	v_add_f32_e32 v164, v164, v165
	ds_bpermute_b32 v151, v230, v150
	ds_bpermute_b32 v153, v230, v152
	ds_bpermute_b32 v155, v230, v154
	ds_bpermute_b32 v157, v230, v156
	ds_bpermute_b32 v159, v230, v158
	ds_bpermute_b32 v161, v230, v160
	ds_bpermute_b32 v163, v230, v162
	ds_bpermute_b32 v165, v230, v164
	s_waitcnt lgkmcnt(0)
	v_add_f32_e32 v150, v150, v151
	v_add_f32_e32 v152, v152, v153
	v_add_f32_e32 v154, v154, v155
	v_add_f32_e32 v156, v156, v157
	v_add_f32_e32 v158, v158, v159
	v_add_f32_e32 v160, v160, v161
	v_add_f32_e32 v162, v162, v163
	v_add_f32_e32 v164, v164, v165
	ds_bpermute_b32 v151, v231, v150
	ds_bpermute_b32 v153, v231, v152
	ds_bpermute_b32 v155, v231, v154
	ds_bpermute_b32 v157, v231, v156
	ds_bpermute_b32 v159, v231, v158
	ds_bpermute_b32 v161, v231, v160
	ds_bpermute_b32 v163, v231, v162
	ds_bpermute_b32 v165, v231, v164
	s_waitcnt lgkmcnt(0)
	v_add_f32_e32 v150, v150, v151
	v_add_f32_e32 v152, v152, v153
	v_add_f32_e32 v154, v154, v155
	v_add_f32_e32 v156, v156, v157
	v_add_f32_e32 v158, v158, v159
	v_add_f32_e32 v160, v160, v161
	v_add_f32_e32 v162, v162, v163
	v_add_f32_e32 v164, v164, v165
	ds_bpermute_b32 v151, v232, v150
	ds_bpermute_b32 v153, v232, v152
	ds_bpermute_b32 v155, v232, v154
	ds_bpermute_b32 v157, v232, v156
	ds_bpermute_b32 v159, v232, v158
	ds_bpermute_b32 v161, v232, v160
	ds_bpermute_b32 v163, v232, v162
	ds_bpermute_b32 v165, v232, v164
	s_waitcnt lgkmcnt(0)
	v_add_f32_e32 v150, v150, v151
	v_add_f32_e32 v152, v152, v153
	v_add_f32_e32 v154, v154, v155
	v_add_f32_e32 v156, v156, v157
	v_add_f32_e32 v158, v158, v159
	v_add_f32_e32 v160, v160, v161
	v_add_f32_e32 v162, v162, v163
	v_add_f32_e32 v164, v164, v165
	v_fmamk_f32 v150, v150, 0x3a800000, v222
	v_fmamk_f32 v152, v152, 0x3a800000, v222
	v_fmamk_f32 v154, v154, 0x3a800000, v222
	v_fmamk_f32 v156, v156, 0x3a800000, v222
	v_fmamk_f32 v158, v158, 0x3a800000, v222
	v_fmamk_f32 v160, v160, 0x3a800000, v222
	v_fmamk_f32 v162, v162, 0x3a800000, v222
	v_fmamk_f32 v164, v164, 0x3a800000, v222
	v_rsq_f32_e32 v150, v150
	v_rsq_f32_e32 v152, v152
	v_rsq_f32_e32 v154, v154
	v_rsq_f32_e32 v156, v156
	v_rsq_f32_e32 v158, v158
	v_rsq_f32_e32 v160, v160
	v_rsq_f32_e32 v162, v162
	v_rsq_f32_e32 v164, v164
	s_waitcnt vmcnt(0)
	v_pk_add_f32 v[132:133], v[132:133], 1.0 op_sel_hi:[1,0]
	v_pk_add_f32 v[134:135], v[134:135], 1.0 op_sel_hi:[1,0]
	v_pk_add_f32 v[136:137], v[136:137], 1.0 op_sel_hi:[1,0]
	v_pk_add_f32 v[138:139], v[138:139], 1.0 op_sel_hi:[1,0]
	v_pk_add_f32 v[140:141], v[140:141], 1.0 op_sel_hi:[1,0]
	v_pk_add_f32 v[142:143], v[142:143], 1.0 op_sel_hi:[1,0]
	v_pk_add_f32 v[144:145], v[144:145], 1.0 op_sel_hi:[1,0]
	v_pk_add_f32 v[146:147], v[146:147], 1.0 op_sel_hi:[1,0]
	v_lshlrev_b32_e32 v166, 16, v84
	v_and_b32_e32 v167, 0xffff0000, v84
	v_lshlrev_b32_e32 v168, 16, v85
	v_and_b32_e32 v169, 0xffff0000, v85
	v_lshlrev_b32_e32 v170, 16, v82
	v_and_b32_e32 v171, 0xffff0000, v82
	v_lshlrev_b32_e32 v172, 16, v83
	v_and_b32_e32 v173, 0xffff0000, v83
	v_lshlrev_b32_e32 v174, 16, v80
	v_and_b32_e32 v175, 0xffff0000, v80
	v_lshlrev_b32_e32 v176, 16, v81
	v_and_b32_e32 v177, 0xffff0000, v81
	v_lshlrev_b32_e32 v178, 16, v38
	v_and_b32_e32 v179, 0xffff0000, v38
	v_lshlrev_b32_e32 v180, 16, v39
	v_and_b32_e32 v181, 0xffff0000, v39
	v_lshl_add_u64 v[184:185], v[182:183], 0, s[34:35]
	v_pk_mul_f32 v[166:167], v[150:151], v[166:167] op_sel_hi:[0,1]
	v_pk_mul_f32 v[168:169], v[150:151], v[168:169] op_sel_hi:[0,1]
	v_pk_mul_f32 v[170:171], v[150:151], v[170:171] op_sel_hi:[0,1]
	v_pk_mul_f32 v[172:173], v[150:151], v[172:173] op_sel_hi:[0,1]
	v_pk_mul_f32 v[174:175], v[150:151], v[174:175] op_sel_hi:[0,1]
	v_pk_mul_f32 v[176:177], v[150:151], v[176:177] op_sel_hi:[0,1]
	v_pk_mul_f32 v[178:179], v[150:151], v[178:179] op_sel_hi:[0,1]
	v_pk_mul_f32 v[180:181], v[150:151], v[180:181] op_sel_hi:[0,1]
	v_pk_mul_f32 v[166:167], v[100:101], v[166:167]
	v_pk_mul_f32 v[168:169], v[102:103], v[168:169]
	v_pk_mul_f32 v[170:171], v[104:105], v[170:171]
	v_pk_mul_f32 v[172:173], v[106:107], v[172:173]
	v_pk_mul_f32 v[174:175], v[108:109], v[174:175]
	v_pk_mul_f32 v[176:177], v[110:111], v[176:177]
	v_pk_mul_f32 v[178:179], v[112:113], v[178:179]
	v_pk_mul_f32 v[180:181], v[114:115], v[180:181]
	v_pk_fma_f32 v[166:167], v[132:133], v[166:167], v[116:117]
	v_pk_fma_f32 v[168:169], v[134:135], v[168:169], v[118:119]
	v_pk_fma_f32 v[170:171], v[136:137], v[170:171], v[120:121]
	v_pk_fma_f32 v[172:173], v[138:139], v[172:173], v[122:123]
	v_pk_fma_f32 v[174:175], v[140:141], v[174:175], v[124:125]
	v_pk_fma_f32 v[176:177], v[142:143], v[176:177], v[126:127]
	v_pk_fma_f32 v[178:179], v[144:145], v[178:179], v[128:129]
	v_pk_fma_f32 v[180:181], v[146:147], v[180:181], v[130:131]
	v_cvt_pk_bf16_f32 v166, v166, v167
	v_cvt_pk_bf16_f32 v167, v168, v169
	v_cvt_pk_bf16_f32 v170, v170, v171
	v_cvt_pk_bf16_f32 v171, v172, v173
	v_cvt_pk_bf16_f32 v174, v174, v175
	v_cvt_pk_bf16_f32 v175, v176, v177
	v_cvt_pk_bf16_f32 v178, v178, v179
	v_cvt_pk_bf16_f32 v179, v180, v181
	global_store_dwordx2 v[184:185], v[166:167], off
	global_store_dwordx2 v[184:185], v[170:171], off offset:512
	global_store_dwordx2 v[184:185], v[174:175], off offset:1024
	global_store_dwordx2 v[184:185], v[178:179], off offset:1536
	v_lshlrev_b32_e32 v166, 16, v78
	v_and_b32_e32 v167, 0xffff0000, v78
	v_lshlrev_b32_e32 v168, 16, v79
	v_and_b32_e32 v169, 0xffff0000, v79
	v_lshlrev_b32_e32 v170, 16, v76
	v_and_b32_e32 v171, 0xffff0000, v76
	v_lshlrev_b32_e32 v172, 16, v77
	v_and_b32_e32 v173, 0xffff0000, v77
	v_lshlrev_b32_e32 v174, 16, v74
	v_and_b32_e32 v175, 0xffff0000, v74
	v_lshlrev_b32_e32 v176, 16, v75
	v_and_b32_e32 v177, 0xffff0000, v75
	v_lshlrev_b32_e32 v178, 16, v72
	v_and_b32_e32 v179, 0xffff0000, v72
	v_lshlrev_b32_e32 v180, 16, v73
	v_and_b32_e32 v181, 0xffff0000, v73
	v_lshl_add_u64 v[184:185], v[182:183], 0, s[30:31]
	v_pk_mul_f32 v[166:167], v[152:153], v[166:167] op_sel_hi:[0,1]
	v_pk_mul_f32 v[168:169], v[152:153], v[168:169] op_sel_hi:[0,1]
	v_pk_mul_f32 v[170:171], v[152:153], v[170:171] op_sel_hi:[0,1]
	v_pk_mul_f32 v[172:173], v[152:153], v[172:173] op_sel_hi:[0,1]
	v_pk_mul_f32 v[174:175], v[152:153], v[174:175] op_sel_hi:[0,1]
	v_pk_mul_f32 v[176:177], v[152:153], v[176:177] op_sel_hi:[0,1]
	v_pk_mul_f32 v[178:179], v[152:153], v[178:179] op_sel_hi:[0,1]
	v_pk_mul_f32 v[180:181], v[152:153], v[180:181] op_sel_hi:[0,1]
	v_pk_mul_f32 v[166:167], v[100:101], v[166:167]
	v_pk_mul_f32 v[168:169], v[102:103], v[168:169]
	v_pk_mul_f32 v[170:171], v[104:105], v[170:171]
	v_pk_mul_f32 v[172:173], v[106:107], v[172:173]
	v_pk_mul_f32 v[174:175], v[108:109], v[174:175]
	v_pk_mul_f32 v[176:177], v[110:111], v[176:177]
	v_pk_mul_f32 v[178:179], v[112:113], v[178:179]
	v_pk_mul_f32 v[180:181], v[114:115], v[180:181]
	v_pk_fma_f32 v[166:167], v[132:133], v[166:167], v[116:117]
	v_pk_fma_f32 v[168:169], v[134:135], v[168:169], v[118:119]
	v_pk_fma_f32 v[170:171], v[136:137], v[170:171], v[120:121]
	v_pk_fma_f32 v[172:173], v[138:139], v[172:173], v[122:123]
	v_pk_fma_f32 v[174:175], v[140:141], v[174:175], v[124:125]
	v_pk_fma_f32 v[176:177], v[142:143], v[176:177], v[126:127]
	v_pk_fma_f32 v[178:179], v[144:145], v[178:179], v[128:129]
	v_pk_fma_f32 v[180:181], v[146:147], v[180:181], v[130:131]
	v_cvt_pk_bf16_f32 v166, v166, v167
	v_cvt_pk_bf16_f32 v167, v168, v169
	v_cvt_pk_bf16_f32 v170, v170, v171
	v_cvt_pk_bf16_f32 v171, v172, v173
	v_cvt_pk_bf16_f32 v174, v174, v175
	v_cvt_pk_bf16_f32 v175, v176, v177
	v_cvt_pk_bf16_f32 v178, v178, v179
	v_cvt_pk_bf16_f32 v179, v180, v181
	global_store_dwordx2 v[184:185], v[166:167], off
	global_store_dwordx2 v[184:185], v[170:171], off offset:512
	global_store_dwordx2 v[184:185], v[174:175], off offset:1024
	global_store_dwordx2 v[184:185], v[178:179], off offset:1536
	v_lshlrev_b32_e32 v166, 16, v70
	v_and_b32_e32 v167, 0xffff0000, v70
	v_lshlrev_b32_e32 v168, 16, v71
	v_and_b32_e32 v169, 0xffff0000, v71
	v_lshlrev_b32_e32 v170, 16, v68
	v_and_b32_e32 v171, 0xffff0000, v68
	v_lshlrev_b32_e32 v172, 16, v69
	v_and_b32_e32 v173, 0xffff0000, v69
	v_lshlrev_b32_e32 v174, 16, v66
	v_and_b32_e32 v175, 0xffff0000, v66
	v_lshlrev_b32_e32 v176, 16, v67
	v_and_b32_e32 v177, 0xffff0000, v67
	v_lshlrev_b32_e32 v178, 16, v64
	v_and_b32_e32 v179, 0xffff0000, v64
	v_lshlrev_b32_e32 v180, 16, v65
	v_and_b32_e32 v181, 0xffff0000, v65
	v_lshl_add_u64 v[184:185], v[182:183], 0, s[14:15]
	v_pk_mul_f32 v[166:167], v[154:155], v[166:167] op_sel_hi:[0,1]
	v_pk_mul_f32 v[168:169], v[154:155], v[168:169] op_sel_hi:[0,1]
	v_pk_mul_f32 v[170:171], v[154:155], v[170:171] op_sel_hi:[0,1]
	v_pk_mul_f32 v[172:173], v[154:155], v[172:173] op_sel_hi:[0,1]
	v_pk_mul_f32 v[174:175], v[154:155], v[174:175] op_sel_hi:[0,1]
	v_pk_mul_f32 v[176:177], v[154:155], v[176:177] op_sel_hi:[0,1]
	v_pk_mul_f32 v[178:179], v[154:155], v[178:179] op_sel_hi:[0,1]
	v_pk_mul_f32 v[180:181], v[154:155], v[180:181] op_sel_hi:[0,1]
	v_pk_mul_f32 v[166:167], v[100:101], v[166:167]
	v_pk_mul_f32 v[168:169], v[102:103], v[168:169]
	v_pk_mul_f32 v[170:171], v[104:105], v[170:171]
	v_pk_mul_f32 v[172:173], v[106:107], v[172:173]
	v_pk_mul_f32 v[174:175], v[108:109], v[174:175]
	v_pk_mul_f32 v[176:177], v[110:111], v[176:177]
	v_pk_mul_f32 v[178:179], v[112:113], v[178:179]
	v_pk_mul_f32 v[180:181], v[114:115], v[180:181]
	v_pk_fma_f32 v[166:167], v[132:133], v[166:167], v[116:117]
	v_pk_fma_f32 v[168:169], v[134:135], v[168:169], v[118:119]
	v_pk_fma_f32 v[170:171], v[136:137], v[170:171], v[120:121]
	v_pk_fma_f32 v[172:173], v[138:139], v[172:173], v[122:123]
	v_pk_fma_f32 v[174:175], v[140:141], v[174:175], v[124:125]
	v_pk_fma_f32 v[176:177], v[142:143], v[176:177], v[126:127]
	v_pk_fma_f32 v[178:179], v[144:145], v[178:179], v[128:129]
	v_pk_fma_f32 v[180:181], v[146:147], v[180:181], v[130:131]
	v_cvt_pk_bf16_f32 v166, v166, v167
	v_cvt_pk_bf16_f32 v167, v168, v169
	v_cvt_pk_bf16_f32 v170, v170, v171
	v_cvt_pk_bf16_f32 v171, v172, v173
	v_cvt_pk_bf16_f32 v174, v174, v175
	v_cvt_pk_bf16_f32 v175, v176, v177
	v_cvt_pk_bf16_f32 v178, v178, v179
	v_cvt_pk_bf16_f32 v179, v180, v181
	global_store_dwordx2 v[184:185], v[166:167], off
	global_store_dwordx2 v[184:185], v[170:171], off offset:512
	global_store_dwordx2 v[184:185], v[174:175], off offset:1024
	global_store_dwordx2 v[184:185], v[178:179], off offset:1536
	v_lshlrev_b32_e32 v166, 16, v62
	v_and_b32_e32 v167, 0xffff0000, v62
	v_lshlrev_b32_e32 v168, 16, v63
	v_and_b32_e32 v169, 0xffff0000, v63
	v_lshlrev_b32_e32 v170, 16, v60
	v_and_b32_e32 v171, 0xffff0000, v60
	v_lshlrev_b32_e32 v172, 16, v61
	v_and_b32_e32 v173, 0xffff0000, v61
	v_lshlrev_b32_e32 v174, 16, v58
	v_and_b32_e32 v175, 0xffff0000, v58
	v_lshlrev_b32_e32 v176, 16, v59
	v_and_b32_e32 v177, 0xffff0000, v59
	v_lshlrev_b32_e32 v178, 16, v56
	v_and_b32_e32 v179, 0xffff0000, v56
	v_lshlrev_b32_e32 v180, 16, v57
	v_and_b32_e32 v181, 0xffff0000, v57
	v_lshl_add_u64 v[184:185], v[182:183], 0, s[26:27]
	v_pk_mul_f32 v[166:167], v[156:157], v[166:167] op_sel_hi:[0,1]
	v_pk_mul_f32 v[168:169], v[156:157], v[168:169] op_sel_hi:[0,1]
	v_pk_mul_f32 v[170:171], v[156:157], v[170:171] op_sel_hi:[0,1]
	v_pk_mul_f32 v[172:173], v[156:157], v[172:173] op_sel_hi:[0,1]
	v_pk_mul_f32 v[174:175], v[156:157], v[174:175] op_sel_hi:[0,1]
	v_pk_mul_f32 v[176:177], v[156:157], v[176:177] op_sel_hi:[0,1]
	v_pk_mul_f32 v[178:179], v[156:157], v[178:179] op_sel_hi:[0,1]
	v_pk_mul_f32 v[180:181], v[156:157], v[180:181] op_sel_hi:[0,1]
	v_pk_mul_f32 v[166:167], v[100:101], v[166:167]
	v_pk_mul_f32 v[168:169], v[102:103], v[168:169]
	v_pk_mul_f32 v[170:171], v[104:105], v[170:171]
	v_pk_mul_f32 v[172:173], v[106:107], v[172:173]
	v_pk_mul_f32 v[174:175], v[108:109], v[174:175]
	v_pk_mul_f32 v[176:177], v[110:111], v[176:177]
	v_pk_mul_f32 v[178:179], v[112:113], v[178:179]
	v_pk_mul_f32 v[180:181], v[114:115], v[180:181]
	v_pk_fma_f32 v[166:167], v[132:133], v[166:167], v[116:117]
	v_pk_fma_f32 v[168:169], v[134:135], v[168:169], v[118:119]
	v_pk_fma_f32 v[170:171], v[136:137], v[170:171], v[120:121]
	v_pk_fma_f32 v[172:173], v[138:139], v[172:173], v[122:123]
	v_pk_fma_f32 v[174:175], v[140:141], v[174:175], v[124:125]
	v_pk_fma_f32 v[176:177], v[142:143], v[176:177], v[126:127]
	v_pk_fma_f32 v[178:179], v[144:145], v[178:179], v[128:129]
	v_pk_fma_f32 v[180:181], v[146:147], v[180:181], v[130:131]
	v_cvt_pk_bf16_f32 v166, v166, v167
	v_cvt_pk_bf16_f32 v167, v168, v169
	v_cvt_pk_bf16_f32 v170, v170, v171
	v_cvt_pk_bf16_f32 v171, v172, v173
	v_cvt_pk_bf16_f32 v174, v174, v175
	v_cvt_pk_bf16_f32 v175, v176, v177
	v_cvt_pk_bf16_f32 v178, v178, v179
	v_cvt_pk_bf16_f32 v179, v180, v181
	global_store_dwordx2 v[184:185], v[166:167], off
	global_store_dwordx2 v[184:185], v[170:171], off offset:512
	global_store_dwordx2 v[184:185], v[174:175], off offset:1024
	global_store_dwordx2 v[184:185], v[178:179], off offset:1536
	v_lshlrev_b32_e32 v166, 16, v54
	v_and_b32_e32 v167, 0xffff0000, v54
	v_lshlrev_b32_e32 v168, 16, v55
	v_and_b32_e32 v169, 0xffff0000, v55
	v_lshlrev_b32_e32 v170, 16, v52
	v_and_b32_e32 v171, 0xffff0000, v52
	v_lshlrev_b32_e32 v172, 16, v53
	v_and_b32_e32 v173, 0xffff0000, v53
	v_lshlrev_b32_e32 v174, 16, v50
	v_and_b32_e32 v175, 0xffff0000, v50
	v_lshlrev_b32_e32 v176, 16, v51
	v_and_b32_e32 v177, 0xffff0000, v51
	v_lshlrev_b32_e32 v178, 16, v48
	v_and_b32_e32 v179, 0xffff0000, v48
	v_lshlrev_b32_e32 v180, 16, v49
	v_and_b32_e32 v181, 0xffff0000, v49
	v_lshl_add_u64 v[184:185], v[182:183], 0, s[24:25]
	v_pk_mul_f32 v[166:167], v[158:159], v[166:167] op_sel_hi:[0,1]
	v_pk_mul_f32 v[168:169], v[158:159], v[168:169] op_sel_hi:[0,1]
	v_pk_mul_f32 v[170:171], v[158:159], v[170:171] op_sel_hi:[0,1]
	v_pk_mul_f32 v[172:173], v[158:159], v[172:173] op_sel_hi:[0,1]
	v_pk_mul_f32 v[174:175], v[158:159], v[174:175] op_sel_hi:[0,1]
	v_pk_mul_f32 v[176:177], v[158:159], v[176:177] op_sel_hi:[0,1]
	v_pk_mul_f32 v[178:179], v[158:159], v[178:179] op_sel_hi:[0,1]
	v_pk_mul_f32 v[180:181], v[158:159], v[180:181] op_sel_hi:[0,1]
	v_pk_mul_f32 v[166:167], v[100:101], v[166:167]
	v_pk_mul_f32 v[168:169], v[102:103], v[168:169]
	v_pk_mul_f32 v[170:171], v[104:105], v[170:171]
	v_pk_mul_f32 v[172:173], v[106:107], v[172:173]
	v_pk_mul_f32 v[174:175], v[108:109], v[174:175]
	v_pk_mul_f32 v[176:177], v[110:111], v[176:177]
	v_pk_mul_f32 v[178:179], v[112:113], v[178:179]
	v_pk_mul_f32 v[180:181], v[114:115], v[180:181]
	v_pk_fma_f32 v[166:167], v[132:133], v[166:167], v[116:117]
	v_pk_fma_f32 v[168:169], v[134:135], v[168:169], v[118:119]
	v_pk_fma_f32 v[170:171], v[136:137], v[170:171], v[120:121]
	v_pk_fma_f32 v[172:173], v[138:139], v[172:173], v[122:123]
	v_pk_fma_f32 v[174:175], v[140:141], v[174:175], v[124:125]
	v_pk_fma_f32 v[176:177], v[142:143], v[176:177], v[126:127]
	v_pk_fma_f32 v[178:179], v[144:145], v[178:179], v[128:129]
	v_pk_fma_f32 v[180:181], v[146:147], v[180:181], v[130:131]
	v_cvt_pk_bf16_f32 v166, v166, v167
	v_cvt_pk_bf16_f32 v167, v168, v169
	v_cvt_pk_bf16_f32 v170, v170, v171
	v_cvt_pk_bf16_f32 v171, v172, v173
	v_cvt_pk_bf16_f32 v174, v174, v175
	v_cvt_pk_bf16_f32 v175, v176, v177
	v_cvt_pk_bf16_f32 v178, v178, v179
	v_cvt_pk_bf16_f32 v179, v180, v181
	global_store_dwordx2 v[184:185], v[166:167], off
	global_store_dwordx2 v[184:185], v[170:171], off offset:512
	global_store_dwordx2 v[184:185], v[174:175], off offset:1024
	global_store_dwordx2 v[184:185], v[178:179], off offset:1536
	v_lshlrev_b32_e32 v166, 16, v46
	v_and_b32_e32 v167, 0xffff0000, v46
	v_lshlrev_b32_e32 v168, 16, v47
	v_and_b32_e32 v169, 0xffff0000, v47
	v_lshlrev_b32_e32 v170, 16, v44
	v_and_b32_e32 v171, 0xffff0000, v44
	v_lshlrev_b32_e32 v172, 16, v45
	v_and_b32_e32 v173, 0xffff0000, v45
	v_lshlrev_b32_e32 v174, 16, v42
	v_and_b32_e32 v175, 0xffff0000, v42
	v_lshlrev_b32_e32 v176, 16, v43
	v_and_b32_e32 v177, 0xffff0000, v43
	v_lshlrev_b32_e32 v178, 16, v40
	v_and_b32_e32 v179, 0xffff0000, v40
	v_lshlrev_b32_e32 v180, 16, v41
	v_and_b32_e32 v181, 0xffff0000, v41
	v_lshl_add_u64 v[184:185], v[182:183], 0, s[22:23]
	v_pk_mul_f32 v[166:167], v[160:161], v[166:167] op_sel_hi:[0,1]
	v_pk_mul_f32 v[168:169], v[160:161], v[168:169] op_sel_hi:[0,1]
	v_pk_mul_f32 v[170:171], v[160:161], v[170:171] op_sel_hi:[0,1]
	v_pk_mul_f32 v[172:173], v[160:161], v[172:173] op_sel_hi:[0,1]
	v_pk_mul_f32 v[174:175], v[160:161], v[174:175] op_sel_hi:[0,1]
	v_pk_mul_f32 v[176:177], v[160:161], v[176:177] op_sel_hi:[0,1]
	v_pk_mul_f32 v[178:179], v[160:161], v[178:179] op_sel_hi:[0,1]
	v_pk_mul_f32 v[180:181], v[160:161], v[180:181] op_sel_hi:[0,1]
	v_pk_mul_f32 v[166:167], v[100:101], v[166:167]
	v_pk_mul_f32 v[168:169], v[102:103], v[168:169]
	v_pk_mul_f32 v[170:171], v[104:105], v[170:171]
	v_pk_mul_f32 v[172:173], v[106:107], v[172:173]
	v_pk_mul_f32 v[174:175], v[108:109], v[174:175]
	v_pk_mul_f32 v[176:177], v[110:111], v[176:177]
	v_pk_mul_f32 v[178:179], v[112:113], v[178:179]
	v_pk_mul_f32 v[180:181], v[114:115], v[180:181]
	v_pk_fma_f32 v[166:167], v[132:133], v[166:167], v[116:117]
	v_pk_fma_f32 v[168:169], v[134:135], v[168:169], v[118:119]
	v_pk_fma_f32 v[170:171], v[136:137], v[170:171], v[120:121]
	v_pk_fma_f32 v[172:173], v[138:139], v[172:173], v[122:123]
	v_pk_fma_f32 v[174:175], v[140:141], v[174:175], v[124:125]
	v_pk_fma_f32 v[176:177], v[142:143], v[176:177], v[126:127]
	v_pk_fma_f32 v[178:179], v[144:145], v[178:179], v[128:129]
	v_pk_fma_f32 v[180:181], v[146:147], v[180:181], v[130:131]
	v_cvt_pk_bf16_f32 v166, v166, v167
	v_cvt_pk_bf16_f32 v167, v168, v169
	v_cvt_pk_bf16_f32 v170, v170, v171
	v_cvt_pk_bf16_f32 v171, v172, v173
	v_cvt_pk_bf16_f32 v174, v174, v175
	v_cvt_pk_bf16_f32 v175, v176, v177
	v_cvt_pk_bf16_f32 v178, v178, v179
	v_cvt_pk_bf16_f32 v179, v180, v181
	global_store_dwordx2 v[184:185], v[166:167], off
	global_store_dwordx2 v[184:185], v[170:171], off offset:512
	global_store_dwordx2 v[184:185], v[174:175], off offset:1024
	global_store_dwordx2 v[184:185], v[178:179], off offset:1536
	v_lshlrev_b32_e32 v166, 16, v36
	v_and_b32_e32 v167, 0xffff0000, v36
	v_lshlrev_b32_e32 v168, 16, v37
	v_and_b32_e32 v169, 0xffff0000, v37
	v_lshlrev_b32_e32 v170, 16, v34
	v_and_b32_e32 v171, 0xffff0000, v34
	v_lshlrev_b32_e32 v172, 16, v35
	v_and_b32_e32 v173, 0xffff0000, v35
	v_lshlrev_b32_e32 v174, 16, v32
	v_and_b32_e32 v175, 0xffff0000, v32
	v_lshlrev_b32_e32 v176, 16, v33
	v_and_b32_e32 v177, 0xffff0000, v33
	v_lshlrev_b32_e32 v178, 16, v30
	v_and_b32_e32 v179, 0xffff0000, v30
	v_lshlrev_b32_e32 v180, 16, v31
	v_and_b32_e32 v181, 0xffff0000, v31
	v_lshl_add_u64 v[184:185], v[182:183], 0, s[12:13]
	v_pk_mul_f32 v[166:167], v[162:163], v[166:167] op_sel_hi:[0,1]
	v_pk_mul_f32 v[168:169], v[162:163], v[168:169] op_sel_hi:[0,1]
	v_pk_mul_f32 v[170:171], v[162:163], v[170:171] op_sel_hi:[0,1]
	v_pk_mul_f32 v[172:173], v[162:163], v[172:173] op_sel_hi:[0,1]
	v_pk_mul_f32 v[174:175], v[162:163], v[174:175] op_sel_hi:[0,1]
	v_pk_mul_f32 v[176:177], v[162:163], v[176:177] op_sel_hi:[0,1]
	v_pk_mul_f32 v[178:179], v[162:163], v[178:179] op_sel_hi:[0,1]
	v_pk_mul_f32 v[180:181], v[162:163], v[180:181] op_sel_hi:[0,1]
	v_pk_mul_f32 v[166:167], v[100:101], v[166:167]
	v_pk_mul_f32 v[168:169], v[102:103], v[168:169]
	v_pk_mul_f32 v[170:171], v[104:105], v[170:171]
	v_pk_mul_f32 v[172:173], v[106:107], v[172:173]
	v_pk_mul_f32 v[174:175], v[108:109], v[174:175]
	v_pk_mul_f32 v[176:177], v[110:111], v[176:177]
	v_pk_mul_f32 v[178:179], v[112:113], v[178:179]
	v_pk_mul_f32 v[180:181], v[114:115], v[180:181]
	v_pk_fma_f32 v[166:167], v[132:133], v[166:167], v[116:117]
	v_pk_fma_f32 v[168:169], v[134:135], v[168:169], v[118:119]
	v_pk_fma_f32 v[170:171], v[136:137], v[170:171], v[120:121]
	v_pk_fma_f32 v[172:173], v[138:139], v[172:173], v[122:123]
	v_pk_fma_f32 v[174:175], v[140:141], v[174:175], v[124:125]
	v_pk_fma_f32 v[176:177], v[142:143], v[176:177], v[126:127]
	v_pk_fma_f32 v[178:179], v[144:145], v[178:179], v[128:129]
	v_pk_fma_f32 v[180:181], v[146:147], v[180:181], v[130:131]
	v_cvt_pk_bf16_f32 v166, v166, v167
	v_cvt_pk_bf16_f32 v167, v168, v169
	v_cvt_pk_bf16_f32 v170, v170, v171
	v_cvt_pk_bf16_f32 v171, v172, v173
	v_cvt_pk_bf16_f32 v174, v174, v175
	v_cvt_pk_bf16_f32 v175, v176, v177
	v_cvt_pk_bf16_f32 v178, v178, v179
	v_cvt_pk_bf16_f32 v179, v180, v181
	global_store_dwordx2 v[184:185], v[166:167], off
	global_store_dwordx2 v[184:185], v[170:171], off offset:512
	global_store_dwordx2 v[184:185], v[174:175], off offset:1024
	global_store_dwordx2 v[184:185], v[178:179], off offset:1536
	v_lshlrev_b32_e32 v166, 16, v26
	v_and_b32_e32 v167, 0xffff0000, v26
	v_lshlrev_b32_e32 v168, 16, v27
	v_and_b32_e32 v169, 0xffff0000, v27
	v_lshlrev_b32_e32 v170, 16, v24
	v_and_b32_e32 v171, 0xffff0000, v24
	v_lshlrev_b32_e32 v172, 16, v25
	v_and_b32_e32 v173, 0xffff0000, v25
	v_lshlrev_b32_e32 v174, 16, v22
	v_and_b32_e32 v175, 0xffff0000, v22
	v_lshlrev_b32_e32 v176, 16, v23
	v_and_b32_e32 v177, 0xffff0000, v23
	v_lshlrev_b32_e32 v178, 16, v20
	v_and_b32_e32 v179, 0xffff0000, v20
	v_lshlrev_b32_e32 v180, 16, v21
	v_and_b32_e32 v181, 0xffff0000, v21
	v_lshl_add_u64 v[184:185], v[182:183], 0, s[8:9]
	v_pk_mul_f32 v[166:167], v[164:165], v[166:167] op_sel_hi:[0,1]
	v_pk_mul_f32 v[168:169], v[164:165], v[168:169] op_sel_hi:[0,1]
	v_pk_mul_f32 v[170:171], v[164:165], v[170:171] op_sel_hi:[0,1]
	v_pk_mul_f32 v[172:173], v[164:165], v[172:173] op_sel_hi:[0,1]
	v_pk_mul_f32 v[174:175], v[164:165], v[174:175] op_sel_hi:[0,1]
	v_pk_mul_f32 v[176:177], v[164:165], v[176:177] op_sel_hi:[0,1]
	v_pk_mul_f32 v[178:179], v[164:165], v[178:179] op_sel_hi:[0,1]
	v_pk_mul_f32 v[180:181], v[164:165], v[180:181] op_sel_hi:[0,1]
	v_pk_mul_f32 v[166:167], v[100:101], v[166:167]
	v_pk_mul_f32 v[168:169], v[102:103], v[168:169]
	v_pk_mul_f32 v[170:171], v[104:105], v[170:171]
	v_pk_mul_f32 v[172:173], v[106:107], v[172:173]
	v_pk_mul_f32 v[174:175], v[108:109], v[174:175]
	v_pk_mul_f32 v[176:177], v[110:111], v[176:177]
	v_pk_mul_f32 v[178:179], v[112:113], v[178:179]
	v_pk_mul_f32 v[180:181], v[114:115], v[180:181]
	v_pk_fma_f32 v[166:167], v[132:133], v[166:167], v[116:117]
	v_pk_fma_f32 v[168:169], v[134:135], v[168:169], v[118:119]
	v_pk_fma_f32 v[170:171], v[136:137], v[170:171], v[120:121]
	v_pk_fma_f32 v[172:173], v[138:139], v[172:173], v[122:123]
	v_pk_fma_f32 v[174:175], v[140:141], v[174:175], v[124:125]
	v_pk_fma_f32 v[176:177], v[142:143], v[176:177], v[126:127]
	v_pk_fma_f32 v[178:179], v[144:145], v[178:179], v[128:129]
	v_pk_fma_f32 v[180:181], v[146:147], v[180:181], v[130:131]
	v_cvt_pk_bf16_f32 v166, v166, v167
	v_cvt_pk_bf16_f32 v167, v168, v169
	v_cvt_pk_bf16_f32 v170, v170, v171
	v_cvt_pk_bf16_f32 v171, v172, v173
	v_cvt_pk_bf16_f32 v174, v174, v175
	v_cvt_pk_bf16_f32 v175, v176, v177
	v_cvt_pk_bf16_f32 v178, v178, v179
	v_cvt_pk_bf16_f32 v179, v180, v181
	global_store_dwordx2 v[184:185], v[166:167], off
	global_store_dwordx2 v[184:185], v[170:171], off offset:512
	global_store_dwordx2 v[184:185], v[174:175], off offset:1024
	global_store_dwordx2 v[184:185], v[178:179], off offset:1536
	v_add_u32_e32 v82, 0xc00, v18
	s_and_b64 vcc, exec, s[0:1]
	s_cbranch_vccnz .LBB0_1127
	v_pk_mul_f32 v[22:23], v[16:17], v[16:17]
	v_pk_mul_f32 v[24:25], v[14:15], v[14:15]
	v_mov_b32_e32 v19, v1
	v_pk_mov_b32 v[26:27], v[24:25], v[22:23] op_sel:[1,0]
	v_mov_b32_e32 v25, v23
	v_pk_add_f32 v[22:23], v[26:27], v[24:25]
	v_pk_mul_f32 v[24:25], v[12:13], v[12:13]
	v_pk_add_f32 v[22:23], v[22:23], v[22:23] op_sel_hi:[0,1]
	v_pk_mul_f32 v[26:27], v[10:11], v[10:11]
	v_lshl_add_u64 v[20:21], v[28:29], 0, v[18:19]
	v_pk_mov_b32 v[28:29], v[26:27], v[24:25] op_sel:[1,0]
	v_mov_b32_e32 v27, v25
	v_mul_f32_e32 v22, v6, v6
	s_add_u32 s8, s3, 0xf000
	v_pk_add_f32 v[24:25], v[28:29], v[26:27]
	v_pk_fma_f32 v[26:27], v[6:7], v[6:7], v[22:23] op_sel_hi:[1,1,0]
	v_mul_f32_e32 v22, v8, v8
	s_addc_u32 s9, s5, 0
	v_pk_fma_f32 v[28:29], v[8:9], v[8:9], v[22:23] op_sel_hi:[1,1,0]
	s_add_u32 s0, s3, 0x10000
	v_mul_f32_e32 v26, v2, v2
	v_mul_f32_e32 v28, v3, v3
	s_addc_u32 s1, s5, 0
	v_pk_add_f32 v[26:27], v[26:27], v[28:29]
	global_load_dwordx4 v[28:31], v[20:21], off
	global_load_dwordx4 v[32:35], v18, s[8:9]
	global_load_dwordx4 v[36:39], v18, s[0:1]
	v_pk_add_f32 v[24:25], v[24:25], v[24:25] op_sel_hi:[0,1]
	v_mul_f32_e32 v24, v4, v4
	v_mul_f32_e32 v22, v5, v5
	v_pk_add_f32 v[22:23], v[24:25], v[22:23]
	s_ashr_i32 s5, s4, 31
	v_pk_add_f32 v[22:23], v[26:27], v[22:23]
	s_lshl_b64 s[4:5], s[4:5], 11
	v_add_f32_e32 v19, v22, v23
	ds_bpermute_b32 v22, v227, v19
	s_add_u32 s4, s10, s4
	s_addc_u32 s5, s11, s5
	v_lshl_add_u64 v[26:27], s[4:5], 0, v[0:1]
	s_brev_b32 s3, 64
	s_waitcnt lgkmcnt(0)
	v_add_f32_e32 v19, v19, v22
	ds_bpermute_b32 v22, v228, v19
	s_mov_b64 s[4:5], 0x2000000
	s_waitcnt lgkmcnt(0)
	v_add_f32_e32 v19, v19, v22
	ds_bpermute_b32 v22, v229, v19
	s_waitcnt lgkmcnt(0)
	v_add_f32_e32 v19, v19, v22
	ds_bpermute_b32 v22, v230, v19
	s_waitcnt lgkmcnt(0)
	v_add_f32_e32 v19, v19, v22
	ds_bpermute_b32 v22, v231, v19
	s_waitcnt lgkmcnt(0)
	v_add_f32_e32 v19, v19, v22
	ds_bpermute_b32 v22, v232, v19
	s_waitcnt lgkmcnt(0)
	v_add_f32_e32 v19, v19, v22
	v_fmamk_f32 v19, v19, 0x3a800000, v222
	v_cmp_gt_f32_e32 vcc, s78, v19
	v_mul_f32_e32 v22, 0x4b800000, v19
	s_nop 0
	v_cndmask_b32_e32 v19, v19, v22, vcc
	v_rsq_f32_e32 v19, v19
	s_nop 0
	v_mul_f32_e32 v22, 0x45800000, v19
	v_cndmask_b32_e32 v24, v19, v22, vcc
	v_pk_mul_f32 v[16:17], v[16:17], v[24:25] op_sel_hi:[1,0]
	v_pk_mul_f32 v[14:15], v[14:15], v[24:25] op_sel_hi:[1,0]
	v_lshl_add_u64 v[22:23], v[26:27], 0, s[4:5]
	v_pk_mul_f32 v[12:13], v[12:13], v[24:25] op_sel_hi:[1,0]
	v_pk_mul_f32 v[10:11], v[10:11], v[24:25] op_sel_hi:[1,0]
	v_pk_mul_f32 v[8:9], v[8:9], v[24:25] op_sel_hi:[1,0]
	v_pk_mul_f32 v[6:7], v[6:7], v[24:25] op_sel_hi:[1,0]
	v_pk_mul_f32 v[4:5], v[4:5], v[24:25] op_sel_hi:[1,0]
	v_pk_mul_f32 v[2:3], v[2:3], v[24:25] op_sel_hi:[1,0]
	s_waitcnt vmcnt(2)
	v_pk_mul_f32 v[14:15], v[28:29], v[14:15]
	v_pk_mul_f32 v[16:17], v[30:31], v[16:17]
	s_waitcnt vmcnt(0)
	v_pk_add_f32 v[18:19], v[38:39], 1.0 op_sel_hi:[1,0]
	v_pk_add_f32 v[28:29], v[36:37], 1.0 op_sel_hi:[1,0]
	v_pk_fma_f32 v[16:17], v[18:19], v[16:17], v[34:35]
	v_pk_fma_f32 v[14:15], v[28:29], v[14:15], v[32:33]
	s_nop 0
	v_cvt_pk_bf16_f32 v14, v14, v15
	v_cvt_pk_bf16_f32 v15, v16, v17
	v_add_co_u32_e32 v16, vcc, s3, v26
	s_nop 1
	v_addc_co_u32_e32 v17, vcc, 0, v27, vcc
	global_store_dwordx2 v[16:17], v[14:15], off
	global_load_dwordx4 v[14:17], v[20:21], off offset:1024
	s_nop 0
	global_load_dwordx4 v[26:29], v92, s[8:9]
	global_load_dwordx4 v[30:33], v92, s[0:1]
	s_waitcnt vmcnt(2)
	v_pk_mul_f32 v[10:11], v[14:15], v[10:11]
	v_pk_mul_f32 v[12:13], v[16:17], v[12:13]
	s_waitcnt vmcnt(0)
	v_pk_add_f32 v[16:17], v[30:31], 1.0 op_sel_hi:[1,0]
	v_pk_add_f32 v[14:15], v[32:33], 1.0 op_sel_hi:[1,0]
	v_pk_fma_f32 v[10:11], v[16:17], v[10:11], v[26:27]
	v_pk_fma_f32 v[12:13], v[14:15], v[12:13], v[28:29]
	v_cvt_pk_bf16_f32 v10, v10, v11
	s_nop 0
	v_cvt_pk_bf16_f32 v11, v12, v13
	global_store_dwordx2 v[22:23], v[10:11], off offset:512
	global_load_dwordx4 v[10:13], v[20:21], off offset:2048
	s_nop 0
	global_load_dwordx4 v[14:17], v88, s[8:9]
	global_load_dwordx4 v[26:29], v88, s[0:1]
	s_waitcnt vmcnt(2)
	v_pk_mul_f32 v[6:7], v[6:7], v[10:11]
	v_pk_mul_f32 v[8:9], v[8:9], v[12:13]
	s_waitcnt vmcnt(0)
	v_pk_add_f32 v[12:13], v[26:27], 1.0 op_sel_hi:[1,0]
	v_pk_add_f32 v[10:11], v[28:29], 1.0 op_sel_hi:[1,0]
	v_pk_fma_f32 v[6:7], v[6:7], v[12:13], v[14:15]
	v_pk_fma_f32 v[8:9], v[8:9], v[10:11], v[16:17]
	v_cvt_pk_bf16_f32 v6, v6, v7
	s_nop 0
	v_cvt_pk_bf16_f32 v7, v8, v9
	global_store_dwordx2 v[22:23], v[6:7], off offset:1024
	global_load_dwordx4 v[6:9], v[20:21], off offset:3072
	s_nop 0
	global_load_dwordx4 v[10:13], v82, s[8:9]
	global_load_dwordx4 v[14:17], v82, s[0:1]
	s_waitcnt vmcnt(2)
	v_pk_mul_f32 v[2:3], v[2:3], v[6:7]
	v_pk_mul_f32 v[4:5], v[4:5], v[8:9]
	s_waitcnt vmcnt(0)
	v_pk_add_f32 v[8:9], v[14:15], 1.0 op_sel_hi:[1,0]
	v_pk_add_f32 v[6:7], v[16:17], 1.0 op_sel_hi:[1,0]
	v_pk_fma_f32 v[2:3], v[2:3], v[8:9], v[10:11]
	v_pk_fma_f32 v[4:5], v[4:5], v[6:7], v[12:13]
	v_cvt_pk_bf16_f32 v2, v2, v3
	s_nop 0
	v_cvt_pk_bf16_f32 v3, v4, v5
	global_store_dwordx2 v[22:23], v[2:3], off offset:1536

.LBB0_1243:
	s_add_u32 s4, s14, 0xfffbe080
	s_addc_u32 s5, s15, -1
	s_add_i32 s2, 0, 0x10000
	s_cmp_eq_u32 s51, 12
	s_cselect_b32 s39, s31, s5
	s_cselect_b32 s38, s69, s4
	s_cselect_b32 s5, s29, s50
	s_cselect_b32 s4, vcc_lo, vcc_hi
	s_add_i32 s44, 0, 0x14000
	v_add_u32_e32 v144, s2, v193
	v_add_u32_e32 v182, s44, v193
	ds_read_b128 v[132:135], v144
	ds_read_b128 v[136:139], v144 offset:1024
	ds_read_b128 v[140:143], v144 offset:2048
	ds_read_b128 v[144:147], v144 offset:3072
	ds_read_b128 v[148:151], v182
	ds_read_b128 v[152:155], v182 offset:1024
	ds_read_b128 v[178:181], v182 offset:2048
	ds_read_b128 v[182:185], v182 offset:3072
	s_mov_b32 s40, 0xfffc0000
	v_lshl_add_u64 v[190:191], s[14:15], 0, v[176:177]
	s_mov_b32 s41, -1
	v_lshl_add_u64 v[208:209], v[190:191], 0, s[40:41]
	s_add_i32 m0, s25, 0xc000
	ds_read_b128 v[186:189], v199
	ds_read_b128 v[200:203], v199 offset:1024
	ds_read_b128 v[204:207], v199 offset:2048
	ds_read_b128 v[214:217], v199 offset:3072
	ds_read_b128 v[234:237], v199 offset:4096
	ds_read_b128 v[238:241], v199 offset:5120
	ds_read_b128 v[242:245], v199 offset:6144
	ds_read_b128 v[246:249], v199 offset:7168
	global_load_lds_dwordx4 v[208:209], off
	s_add_i32 m0, s25, 0xe000
	s_nop 0
	global_load_lds_dwordx4 v[190:191], off
	s_waitcnt vmcnt(8)
	s_waitcnt lgkmcnt(0)
	s_barrier
	s_setprio 1
	s_waitcnt lgkmcnt(0)
	v_mfma_f32_16x16x32_bf16 v[64:67], v[132:135], v[186:189], v[64:67]
	v_mfma_f32_16x16x32_bf16 v[56:59], v[140:143], v[186:189], v[56:59]
	v_mfma_f32_16x16x32_bf16 v[60:63], v[132:135], v[204:207], v[60:63]
	v_mfma_f32_16x16x32_bf16 v[20:23], v[140:143], v[204:207], v[20:23]
	v_mfma_f32_16x16x32_bf16 v[128:131], v[132:135], v[234:237], v[128:131]
	v_mfma_f32_16x16x32_bf16 v[96:99], v[140:143], v[234:237], v[96:99]
	v_mfma_f32_16x16x32_bf16 v[124:127], v[132:135], v[242:245], v[124:127]
	v_mfma_f32_16x16x32_bf16 v[92:95], v[140:143], v[242:245], v[92:95]
	v_mfma_f32_16x16x32_bf16 v[64:67], v[136:139], v[200:203], v[64:67]
	v_mfma_f32_16x16x32_bf16 v[56:59], v[144:147], v[200:203], v[56:59]
	v_mfma_f32_16x16x32_bf16 v[60:63], v[136:139], v[214:217], v[60:63]
	v_mfma_f32_16x16x32_bf16 v[20:23], v[144:147], v[214:217], v[20:23]
	v_mfma_f32_16x16x32_bf16 v[128:131], v[136:139], v[238:241], v[128:131]
	v_mfma_f32_16x16x32_bf16 v[96:99], v[144:147], v[238:241], v[96:99]
	v_mfma_f32_16x16x32_bf16 v[124:127], v[136:139], v[246:249], v[124:127]
	v_mfma_f32_16x16x32_bf16 v[92:95], v[144:147], v[246:249], v[92:95]
	s_setprio 0
	s_setprio 1
	v_mfma_f32_16x16x32_bf16 v[48:51], v[148:151], v[186:189], v[48:51]
	v_mfma_f32_16x16x32_bf16 v[4:7], v[178:181], v[186:189], v[4:7]
	v_mfma_f32_16x16x32_bf16 v[44:47], v[148:151], v[204:207], v[44:47]
	v_mfma_f32_16x16x32_bf16 v[8:11], v[178:181], v[204:207], v[8:11]
	v_mfma_f32_16x16x32_bf16 v[120:123], v[148:151], v[234:237], v[120:123]
	v_mfma_f32_16x16x32_bf16 v[88:91], v[178:181], v[234:237], v[88:91]
	v_mfma_f32_16x16x32_bf16 v[112:115], v[148:151], v[242:245], v[112:115]
	v_mfma_f32_16x16x32_bf16 v[80:83], v[178:181], v[242:245], v[80:83]
	v_mfma_f32_16x16x32_bf16 v[48:51], v[152:155], v[200:203], v[48:51]
	v_mfma_f32_16x16x32_bf16 v[4:7], v[182:185], v[200:203], v[4:7]
	v_mfma_f32_16x16x32_bf16 v[44:47], v[152:155], v[214:217], v[44:47]
	v_mfma_f32_16x16x32_bf16 v[8:11], v[182:185], v[214:217], v[8:11]
	v_mfma_f32_16x16x32_bf16 v[120:123], v[152:155], v[238:241], v[120:123]
	v_mfma_f32_16x16x32_bf16 v[88:91], v[182:185], v[238:241], v[88:91]
	v_mfma_f32_16x16x32_bf16 v[112:115], v[152:155], v[246:249], v[112:115]
	v_mfma_f32_16x16x32_bf16 v[80:83], v[182:185], v[246:249], v[80:83]
	s_setprio 0
	s_barrier
	s_add_i32 s2, s2, s72
	v_lshl_add_u64 v[190:191], s[4:5], 0, v[0:1]
	s_mov_b32 m0, s2
	ds_read_b128 v[186:189], v199 offset:16384
	ds_read_b128 v[200:203], v199 offset:17408
	ds_read_b128 v[204:207], v199 offset:18432
	ds_read_b128 v[214:217], v199 offset:19456
	ds_read_b128 v[234:237], v199 offset:20480
	ds_read_b128 v[238:241], v199 offset:21504
	ds_read_b128 v[242:245], v199 offset:22528
	ds_read_b128 v[246:249], v199 offset:23552
	global_load_lds_dwordx4 v[190:191], off
	v_lshl_add_u64 v[208:209], v[190:191], 0, s[88:89]
	s_add_i32 m0, s2, 0x2000
	s_add_i32 s2, s44, s72
	global_load_lds_dwordx4 v[208:209], off
	v_lshl_add_u64 v[208:209], v[190:191], 0, s[90:91]
	s_mov_b32 m0, s2
	s_nop 0
	global_load_lds_dwordx4 v[208:209], off
	v_lshl_add_u64 v[208:209], v[190:191], 0, s[92:93]
	s_add_i32 m0, s2, 0x2000
	s_nop 0
	global_load_lds_dwordx4 v[208:209], off
	v_lshl_add_u64 v[208:209], s[38:39], 0, v[162:163]
	s_mov_b32 m0, s25
	v_lshl_add_u64 v[218:219], v[208:209], 0, s[96:97]
	global_load_lds_dwordx4 v[208:209], off
	s_mov_b32 m0, s78
	s_nop 0
	global_load_lds_dwordx4 v[218:219], off
	s_waitcnt vmcnt(8)
	s_waitcnt lgkmcnt(0)
	s_barrier
	s_setprio 1
	s_waitcnt lgkmcnt(0)
	v_mfma_f32_16x16x32_bf16 v[116:119], v[132:135], v[186:189], v[116:119]
	v_mfma_f32_16x16x32_bf16 v[84:87], v[140:143], v[186:189], v[84:87]
	v_mfma_f32_16x16x32_bf16 v[108:111], v[132:135], v[204:207], v[108:111]
	v_mfma_f32_16x16x32_bf16 v[76:79], v[140:143], v[204:207], v[76:79]
	v_mfma_f32_16x16x32_bf16 v[52:55], v[132:135], v[234:237], v[52:55]
	v_mfma_f32_16x16x32_bf16 v[36:39], v[140:143], v[234:237], v[36:39]
	v_mfma_f32_16x16x32_bf16 v[40:43], v[132:135], v[242:245], v[40:43]
	v_mfma_f32_16x16x32_bf16 v[28:31], v[140:143], v[242:245], v[28:31]
	v_mfma_f32_16x16x32_bf16 v[116:119], v[136:139], v[200:203], v[116:119]
	v_mfma_f32_16x16x32_bf16 v[84:87], v[144:147], v[200:203], v[84:87]
	v_mfma_f32_16x16x32_bf16 v[108:111], v[136:139], v[214:217], v[108:111]
	v_mfma_f32_16x16x32_bf16 v[76:79], v[144:147], v[214:217], v[76:79]
	v_mfma_f32_16x16x32_bf16 v[52:55], v[136:139], v[238:241], v[52:55]
	v_mfma_f32_16x16x32_bf16 v[36:39], v[144:147], v[238:241], v[36:39]
	v_mfma_f32_16x16x32_bf16 v[40:43], v[136:139], v[246:249], v[40:43]
	v_mfma_f32_16x16x32_bf16 v[28:31], v[144:147], v[246:249], v[28:31]
	s_setprio 0
	s_setprio 1
	v_mfma_f32_16x16x32_bf16 v[104:107], v[148:151], v[186:189], v[104:107]
	v_mfma_f32_16x16x32_bf16 v[72:75], v[178:181], v[186:189], v[72:75]
	v_mfma_f32_16x16x32_bf16 v[100:103], v[148:151], v[204:207], v[100:103]
	v_mfma_f32_16x16x32_bf16 v[68:71], v[178:181], v[204:207], v[68:71]
	v_mfma_f32_16x16x32_bf16 v[32:35], v[148:151], v[234:237], v[32:35]
	v_mfma_f32_16x16x32_bf16 v[12:15], v[178:181], v[234:237], v[12:15]
	v_mfma_f32_16x16x32_bf16 v[24:27], v[148:151], v[242:245], v[24:27]
	v_mfma_f32_16x16x32_bf16 v[16:19], v[178:181], v[242:245], v[16:19]
	v_mfma_f32_16x16x32_bf16 v[104:107], v[152:155], v[200:203], v[104:107]
	v_mfma_f32_16x16x32_bf16 v[72:75], v[182:185], v[200:203], v[72:75]
	v_mfma_f32_16x16x32_bf16 v[100:103], v[152:155], v[214:217], v[100:103]
	v_mfma_f32_16x16x32_bf16 v[68:71], v[182:185], v[214:217], v[68:71]
	v_mfma_f32_16x16x32_bf16 v[32:35], v[152:155], v[238:241], v[32:35]
	v_mfma_f32_16x16x32_bf16 v[12:15], v[182:185], v[238:241], v[12:15]
	v_mfma_f32_16x16x32_bf16 v[24:27], v[152:155], v[246:249], v[24:27]
	v_mfma_f32_16x16x32_bf16 v[16:19], v[182:185], v[246:249], v[16:19]
	s_setprio 0
	s_barrier
	s_add_i32 s2, 0, 0x18000
	s_add_i32 s4, 0, 0x1c000
	v_add_u32_e32 v144, s2, v193
	v_add_u32_e32 v182, s4, v193
	ds_read_b128 v[132:135], v144
	ds_read_b128 v[136:139], v144 offset:1024
	ds_read_b128 v[140:143], v144 offset:2048
	ds_read_b128 v[144:147], v144 offset:3072
	ds_read_b128 v[148:151], v182
	ds_read_b128 v[152:155], v182 offset:1024
	ds_read_b128 v[178:181], v182 offset:2048
	ds_read_b128 v[182:185], v182 offset:3072
	s_mov_b32 m0, s79
	v_lshl_add_u64 v[218:219], v[208:209], 0, s[88:89]
	ds_read_b128 v[186:189], v199 offset:32768
	ds_read_b128 v[200:203], v199 offset:33792
	ds_read_b128 v[204:207], v199 offset:34816
	ds_read_b128 v[214:217], v199 offset:35840
	ds_read_b128 v[234:237], v199 offset:36864
	ds_read_b128 v[238:241], v199 offset:37888
	ds_read_b128 v[242:245], v199 offset:38912
	ds_read_b128 v[246:249], v199 offset:39936
	global_load_lds_dwordx4 v[218:219], off
	v_lshl_add_u64 v[218:219], v[208:209], 0, s[52:53]
	s_mov_b32 m0, s6
	s_nop 0
	global_load_lds_dwordx4 v[218:219], off
	s_waitcnt vmcnt(8)
	s_waitcnt lgkmcnt(0)
	s_barrier
	s_setprio 1
	s_waitcnt lgkmcnt(0)
	v_mfma_f32_16x16x32_bf16 v[64:67], v[132:135], v[186:189], v[64:67]
	v_mfma_f32_16x16x32_bf16 v[56:59], v[140:143], v[186:189], v[56:59]
	v_mfma_f32_16x16x32_bf16 v[60:63], v[132:135], v[204:207], v[60:63]
	v_mfma_f32_16x16x32_bf16 v[20:23], v[140:143], v[204:207], v[20:23]
	v_mfma_f32_16x16x32_bf16 v[128:131], v[132:135], v[234:237], v[128:131]
	v_mfma_f32_16x16x32_bf16 v[96:99], v[140:143], v[234:237], v[96:99]
	v_mfma_f32_16x16x32_bf16 v[124:127], v[132:135], v[242:245], v[124:127]
	v_mfma_f32_16x16x32_bf16 v[92:95], v[140:143], v[242:245], v[92:95]
	v_mfma_f32_16x16x32_bf16 v[64:67], v[136:139], v[200:203], v[64:67]
	v_mfma_f32_16x16x32_bf16 v[56:59], v[144:147], v[200:203], v[56:59]
	v_mfma_f32_16x16x32_bf16 v[60:63], v[136:139], v[214:217], v[60:63]
	v_mfma_f32_16x16x32_bf16 v[20:23], v[144:147], v[214:217], v[20:23]
	v_mfma_f32_16x16x32_bf16 v[128:131], v[136:139], v[238:241], v[128:131]
	v_mfma_f32_16x16x32_bf16 v[96:99], v[144:147], v[238:241], v[96:99]
	v_mfma_f32_16x16x32_bf16 v[124:127], v[136:139], v[246:249], v[124:127]
	v_mfma_f32_16x16x32_bf16 v[92:95], v[144:147], v[246:249], v[92:95]
	s_setprio 0
	s_setprio 1
	v_mfma_f32_16x16x32_bf16 v[48:51], v[148:151], v[186:189], v[48:51]
	v_mfma_f32_16x16x32_bf16 v[4:7], v[178:181], v[186:189], v[4:7]
	v_mfma_f32_16x16x32_bf16 v[44:47], v[148:151], v[204:207], v[44:47]
	v_mfma_f32_16x16x32_bf16 v[8:11], v[178:181], v[204:207], v[8:11]
	v_mfma_f32_16x16x32_bf16 v[120:123], v[148:151], v[234:237], v[120:123]
	v_mfma_f32_16x16x32_bf16 v[88:91], v[178:181], v[234:237], v[88:91]
	v_mfma_f32_16x16x32_bf16 v[112:115], v[148:151], v[242:245], v[112:115]
	v_mfma_f32_16x16x32_bf16 v[80:83], v[178:181], v[242:245], v[80:83]
	v_mfma_f32_16x16x32_bf16 v[48:51], v[152:155], v[200:203], v[48:51]
	v_mfma_f32_16x16x32_bf16 v[4:7], v[182:185], v[200:203], v[4:7]
	v_mfma_f32_16x16x32_bf16 v[44:47], v[152:155], v[214:217], v[44:47]
	v_mfma_f32_16x16x32_bf16 v[8:11], v[182:185], v[214:217], v[8:11]
	v_mfma_f32_16x16x32_bf16 v[120:123], v[152:155], v[238:241], v[120:123]
	v_mfma_f32_16x16x32_bf16 v[88:91], v[182:185], v[238:241], v[88:91]
	v_mfma_f32_16x16x32_bf16 v[112:115], v[152:155], v[246:249], v[112:115]
	v_mfma_f32_16x16x32_bf16 v[80:83], v[182:185], v[246:249], v[80:83]
	s_setprio 0
	s_barrier
	s_add_i32 s2, s2, s72
	v_lshl_add_u64 v[218:219], v[190:191], 0, s[64:65]
	s_mov_b32 m0, s2
	ds_read_b128 v[186:189], v199 offset:49152
	ds_read_b128 v[200:203], v199 offset:50176
	ds_read_b128 v[204:207], v199 offset:51200
	ds_read_b128 v[214:217], v199 offset:52224
	ds_read_b128 v[234:237], v199 offset:53248
	ds_read_b128 v[238:241], v199 offset:54272
	ds_read_b128 v[242:245], v199 offset:55296
	ds_read_b128 v[246:249], v199 offset:56320
	global_load_lds_dwordx4 v[218:219], off
	v_lshl_add_u64 v[218:219], v[190:191], 0, s[62:63]
	s_add_i32 m0, s2, 0x2000
	s_add_i32 s2, s4, s72
	global_load_lds_dwordx4 v[218:219], off
	v_lshl_add_u64 v[218:219], v[190:191], 0, s[56:57]
	s_mov_b32 m0, s2
	v_lshl_add_u64 v[190:191], v[190:191], 0, s[58:59]
	global_load_lds_dwordx4 v[218:219], off
	s_add_i32 m0, s2, 0x2000
	s_nop 0
	global_load_lds_dwordx4 v[190:191], off
	v_lshl_add_u64 v[190:191], v[208:209], 0, s[66:67]
	s_mov_b32 m0, s7
	s_nop 0
	global_load_lds_dwordx4 v[190:191], off
	v_lshl_add_u64 v[190:191], v[208:209], 0, s[70:71]
	s_mov_b32 m0, s16
	s_nop 0
	global_load_lds_dwordx4 v[190:191], off
	s_waitcnt vmcnt(8)
	s_waitcnt lgkmcnt(0)
	s_barrier
	s_setprio 1
	s_waitcnt lgkmcnt(0)
	v_mfma_f32_16x16x32_bf16 v[116:119], v[132:135], v[186:189], v[116:119]
	v_mfma_f32_16x16x32_bf16 v[84:87], v[140:143], v[186:189], v[84:87]
	v_mfma_f32_16x16x32_bf16 v[108:111], v[132:135], v[204:207], v[108:111]
	v_mfma_f32_16x16x32_bf16 v[76:79], v[140:143], v[204:207], v[76:79]
	v_mfma_f32_16x16x32_bf16 v[52:55], v[132:135], v[234:237], v[52:55]
	v_mfma_f32_16x16x32_bf16 v[36:39], v[140:143], v[234:237], v[36:39]
	v_mfma_f32_16x16x32_bf16 v[40:43], v[132:135], v[242:245], v[40:43]
	v_mfma_f32_16x16x32_bf16 v[28:31], v[140:143], v[242:245], v[28:31]
	v_mfma_f32_16x16x32_bf16 v[116:119], v[136:139], v[200:203], v[116:119]
	v_mfma_f32_16x16x32_bf16 v[84:87], v[144:147], v[200:203], v[84:87]
	v_mfma_f32_16x16x32_bf16 v[108:111], v[136:139], v[214:217], v[108:111]
	v_mfma_f32_16x16x32_bf16 v[76:79], v[144:147], v[214:217], v[76:79]
	v_mfma_f32_16x16x32_bf16 v[52:55], v[136:139], v[238:241], v[52:55]
	v_mfma_f32_16x16x32_bf16 v[36:39], v[144:147], v[238:241], v[36:39]
	v_mfma_f32_16x16x32_bf16 v[40:43], v[136:139], v[246:249], v[40:43]
	v_mfma_f32_16x16x32_bf16 v[28:31], v[144:147], v[246:249], v[28:31]
	s_setprio 0
	s_setprio 1
	v_mfma_f32_16x16x32_bf16 v[104:107], v[148:151], v[186:189], v[104:107]
	v_mfma_f32_16x16x32_bf16 v[72:75], v[178:181], v[186:189], v[72:75]
	v_mfma_f32_16x16x32_bf16 v[100:103], v[148:151], v[204:207], v[100:103]
	v_mfma_f32_16x16x32_bf16 v[68:71], v[178:181], v[204:207], v[68:71]
	v_mfma_f32_16x16x32_bf16 v[32:35], v[148:151], v[234:237], v[32:35]
	v_mfma_f32_16x16x32_bf16 v[12:15], v[178:181], v[234:237], v[12:15]
	v_mfma_f32_16x16x32_bf16 v[24:27], v[148:151], v[242:245], v[24:27]
	v_mfma_f32_16x16x32_bf16 v[16:19], v[178:181], v[242:245], v[16:19]
	v_mfma_f32_16x16x32_bf16 v[104:107], v[152:155], v[200:203], v[104:107]
	v_mfma_f32_16x16x32_bf16 v[72:75], v[182:185], v[200:203], v[72:75]
	v_mfma_f32_16x16x32_bf16 v[100:103], v[152:155], v[214:217], v[100:103]
	v_mfma_f32_16x16x32_bf16 v[68:71], v[182:185], v[214:217], v[68:71]
	v_mfma_f32_16x16x32_bf16 v[32:35], v[152:155], v[238:241], v[32:35]
	v_mfma_f32_16x16x32_bf16 v[12:15], v[182:185], v[238:241], v[12:15]
	v_mfma_f32_16x16x32_bf16 v[24:27], v[152:155], v[246:249], v[24:27]
	v_mfma_f32_16x16x32_bf16 v[16:19], v[182:185], v[246:249], v[16:19]
	s_setprio 0
	s_barrier
	s_add_i32 s51, s51, 2
	s_add_u32 vcc_hi, vcc_hi, 0x10000
	s_addc_u32 s50, s50, 0
	s_add_u32 s14, s14, 0x100
	s_addc_u32 s15, s15, 0
	s_cmp_gt_u32 s51, 13
	s_cbranch_scc0 .LBB0_1243
	v_lshl_or_b32 v178, s68, 7, v198
	v_mov_b32_e32 v179, 0
	v_lshlrev_b32_e32 v180, 2, v178
	v_mov_b32_e32 v181, 0
	v_lshl_add_u64 v[182:183], v[164:165], 0, v[180:181]
	global_load_dwordx4 v[132:135], v[182:183], off
	global_load_dwordx4 v[234:237], v[182:183], off offset:16
	v_lshl_add_u64 v[184:185], v[166:167], 0, v[180:181]
	global_load_dwordx4 v[136:139], v[184:185], off
	global_load_dwordx4 v[238:241], v[184:185], off offset:16
	v_lshl_add_u64 v[186:187], v[168:169], 0, v[180:181]
	global_load_dwordx4 v[140:143], v[186:187], off
	global_load_dwordx4 v[242:245], v[186:187], off offset:16
	v_lshl_add_u64 v[188:189], v[170:171], 0, v[180:181]
	global_load_dwordx4 v[144:147], v[188:189], off
	global_load_dwordx4 v[246:249], v[188:189], off offset:16
	v_lshl_add_u64 v[190:191], v[172:173], 0, v[180:181]
	global_load_dwordx4 v[148:151], v[190:191], off
	global_load_dwordx4 v[200:203], v[190:191], off offset:16
	v_lshl_add_u64 v[208:209], v[174:175], 0, v[180:181]
	global_load_dwordx4 v[152:155], v[208:209], off
	global_load_dwordx4 v[204:207], v[208:209], off offset:16
	s_and_b64 vcc, exec, s[26:27]
	s_cbranch_vccz .LBB0_1246
	s_barrier
.LBB0_1246:
	v_readlane_b32 s69, v254, 62
	v_readlane_b32 s50, v255, 0
	v_readlane_b32 s51, v255, 1
	s_mov_b32 s44, s0
	v_lshl_add_u32 v184, s24, 3, v195
	s_movk_i32 s2, 0x5800
	v_mov_b64_e32 v[182:183], s[22:23]
	v_mad_i64_i32 v[182:183], s[14:15], v184, s2, v[182:183]
	v_lshl_add_u64 v[182:183], v[178:179], 2, v[182:183]
	s_mov_b64 s[4:5], 0x2c00
	v_lshl_add_u64 v[184:185], v[182:183], 0, s[4:5]
	s_mov_b64 s[4:5], 0x5800
	v_lshl_add_u64 v[186:187], v[182:183], 0, s[4:5]
	s_mov_b64 s[4:5], 0x8400
	v_lshl_add_u64 v[188:189], v[182:183], 0, s[4:5]
	v_lshl_add_u32 v190, s24, 8, v194
	s_movk_i32 s2, 0x1600
	v_mov_b64_e32 v[214:215], s[20:21]
	v_mad_i64_i32 v[214:215], s[14:15], v190, s2, v[214:215]
	v_lshl_add_u64 v[214:215], v[178:179], 1, v[214:215]
	s_mov_b32 s100, 0xbfb8aa3b
	s_mov_b64 s[38:39], exec
	s_mov_b64 exec, s[10:11]
	global_store_dwordx4 v[182:183], v[64:67], off
	global_store_dwordx4 v[182:183], v[56:59], off offset:16
	global_store_dwordx4 v[184:185], v[48:51], off
	global_store_dwordx4 v[184:185], v[4:7], off offset:16
	global_store_dwordx4 v[186:187], v[60:63], off
	global_store_dwordx4 v[186:187], v[20:23], off offset:16
	global_store_dwordx4 v[188:189], v[44:47], off
	global_store_dwordx4 v[188:189], v[8:11], off offset:16
	s_mov_b64 exec, s[8:9]
	global_store_dwordx4 v[182:183], v[52:55], off
	global_store_dwordx4 v[182:183], v[36:39], off offset:16
	global_store_dwordx4 v[184:185], v[32:35], off
	global_store_dwordx4 v[184:185], v[12:15], off offset:16
	global_store_dwordx4 v[186:187], v[40:43], off
	global_store_dwordx4 v[186:187], v[28:31], off offset:16
	global_store_dwordx4 v[188:189], v[24:27], off
	global_store_dwordx4 v[188:189], v[16:19], off offset:16
	s_mov_b64 exec, s[38:39]
	s_waitcnt vmcnt(16)
	v_mul_f32_dpp v188, v24, v144 row_shr:1 row_mask:0xf bank_mask:0xf bound_ctrl:1
	v_mul_f32_dpp v189, v25, v145 row_shr:1 row_mask:0xf bank_mask:0xf bound_ctrl:1
	v_mul_f32_dpp v190, v26, v146 row_shr:1 row_mask:0xf bank_mask:0xf bound_ctrl:1
	v_mul_f32_dpp v191, v27, v147 row_shr:1 row_mask:0xf bank_mask:0xf bound_ctrl:1
	v_mul_f32_dpp v178, v16, v246 row_shr:1 row_mask:0xf bank_mask:0xf bound_ctrl:1
	v_mul_f32_dpp v179, v17, v247 row_shr:1 row_mask:0xf bank_mask:0xf bound_ctrl:1
	v_mul_f32_dpp v208, v18, v248 row_shr:1 row_mask:0xf bank_mask:0xf bound_ctrl:1
	v_mul_f32_dpp v209, v19, v249 row_shr:1 row_mask:0xf bank_mask:0xf bound_ctrl:1
	v_pk_fma_f32 v[188:189], v[48:49], v[148:149], v[188:189]
	v_pk_fma_f32 v[190:191], v[50:51], v[150:151], v[190:191]
	v_pk_fma_f32 v[178:179], v[4:5], v[200:201], v[178:179]
	v_pk_fma_f32 v[208:209], v[6:7], v[202:203], v[208:209]
	v_pk_fma_f32 v[188:189], v[44:45], v[152:153], v[188:189]
	v_pk_fma_f32 v[190:191], v[46:47], v[154:155], v[190:191]
	v_pk_fma_f32 v[178:179], v[8:9], v[204:205], v[178:179]
	v_pk_fma_f32 v[208:209], v[10:11], v[206:207], v[208:209]
	v_pk_mul_f32 v[180:181], v[188:189], s[100:101] op_sel_hi:[1,0]
	v_pk_mul_f32 v[182:183], v[190:191], s[100:101] op_sel_hi:[1,0]
	v_pk_mul_f32 v[184:185], v[178:179], s[100:101] op_sel_hi:[1,0]
	v_pk_mul_f32 v[186:187], v[208:209], s[100:101] op_sel_hi:[1,0]
	v_exp_f32_e32 v180, v180
	v_exp_f32_e32 v181, v181
	v_exp_f32_e32 v182, v182
	v_exp_f32_e32 v183, v183
	v_exp_f32_e32 v184, v184
	v_exp_f32_e32 v185, v185
	v_exp_f32_e32 v186, v186
	v_exp_f32_e32 v187, v187
	v_pk_add_f32 v[180:181], v[180:181], 1.0 op_sel_hi:[1,0]
	v_pk_add_f32 v[182:183], v[182:183], 1.0 op_sel_hi:[1,0]
	v_pk_add_f32 v[184:185], v[184:185], 1.0 op_sel_hi:[1,0]
	v_pk_add_f32 v[186:187], v[186:187], 1.0 op_sel_hi:[1,0]
	v_rcp_f32_e32 v180, v180
	v_rcp_f32_e32 v181, v181
	v_rcp_f32_e32 v182, v182
	v_rcp_f32_e32 v183, v183
	v_rcp_f32_e32 v184, v184
	v_rcp_f32_e32 v185, v185
	v_rcp_f32_e32 v186, v186
	v_rcp_f32_e32 v187, v187
	v_pk_mul_f32 v[188:189], v[188:189], v[180:181]
	v_pk_mul_f32 v[190:191], v[190:191], v[182:183]
	v_pk_mul_f32 v[178:179], v[178:179], v[184:185]
	v_pk_mul_f32 v[208:209], v[208:209], v[186:187]
	v_mul_f32_dpp v180, v40, v132 row_shr:1 row_mask:0xf bank_mask:0xf bound_ctrl:1
	v_mul_f32_dpp v181, v41, v133 row_shr:1 row_mask:0xf bank_mask:0xf bound_ctrl:1
	v_mul_f32_dpp v182, v42, v134 row_shr:1 row_mask:0xf bank_mask:0xf bound_ctrl:1
	v_mul_f32_dpp v183, v43, v135 row_shr:1 row_mask:0xf bank_mask:0xf bound_ctrl:1
	v_mul_f32_dpp v184, v28, v234 row_shr:1 row_mask:0xf bank_mask:0xf bound_ctrl:1
	v_mul_f32_dpp v185, v29, v235 row_shr:1 row_mask:0xf bank_mask:0xf bound_ctrl:1
	v_mul_f32_dpp v186, v30, v236 row_shr:1 row_mask:0xf bank_mask:0xf bound_ctrl:1
	v_mul_f32_dpp v187, v31, v237 row_shr:1 row_mask:0xf bank_mask:0xf bound_ctrl:1
	v_pk_fma_f32 v[180:181], v[64:65], v[136:137], v[180:181]
	v_pk_fma_f32 v[182:183], v[66:67], v[138:139], v[182:183]
	v_pk_fma_f32 v[184:185], v[56:57], v[238:239], v[184:185]
	v_pk_fma_f32 v[186:187], v[58:59], v[240:241], v[186:187]
	v_pk_fma_f32 v[180:181], v[60:61], v[140:141], v[180:181]
	v_pk_fma_f32 v[182:183], v[62:63], v[142:143], v[182:183]
	v_pk_fma_f32 v[184:185], v[20:21], v[242:243], v[184:185]
	v_pk_fma_f32 v[186:187], v[22:23], v[244:245], v[186:187]
	v_pk_mul_f32 v[180:181], v[180:181], v[188:189]
	v_pk_mul_f32 v[182:183], v[182:183], v[190:191]
	v_pk_mul_f32 v[184:185], v[184:185], v[178:179]
	v_pk_mul_f32 v[186:187], v[186:187], v[208:209]
	v_cvt_pk_bf16_f32 v216, v180, v181
	v_cvt_pk_bf16_f32 v217, v182, v183
	v_cvt_pk_bf16_f32 v218, v184, v185
	v_cvt_pk_bf16_f32 v219, v186, v187
	global_store_dwordx4 v[214:215], v[216:219], off
	s_mov_b32 s4, 0x9a00
	s_mov_b32 s5, 0
	v_lshl_add_u64 v[214:215], v[214:215], 0, s[4:5]
	v_pk_mul_f32 v[188:189], v[32:33], v[144:145]
	v_pk_mul_f32 v[190:191], v[34:35], v[146:147]
	v_pk_mul_f32 v[178:179], v[12:13], v[246:247]
	v_pk_mul_f32 v[208:209], v[14:15], v[248:249]
	v_pk_fma_f32 v[188:189], v[24:25], v[148:149], v[188:189]
	v_pk_fma_f32 v[190:191], v[26:27], v[150:151], v[190:191]
	v_pk_fma_f32 v[178:179], v[16:17], v[200:201], v[178:179]
	v_pk_fma_f32 v[208:209], v[18:19], v[202:203], v[208:209]
	v_fmac_f32_dpp v188, v48, v152 row_shl:1 row_mask:0xf bank_mask:0xf bound_ctrl:1
	v_fmac_f32_dpp v189, v49, v153 row_shl:1 row_mask:0xf bank_mask:0xf bound_ctrl:1
	v_fmac_f32_dpp v190, v50, v154 row_shl:1 row_mask:0xf bank_mask:0xf bound_ctrl:1
	v_fmac_f32_dpp v191, v51, v155 row_shl:1 row_mask:0xf bank_mask:0xf bound_ctrl:1
	v_fmac_f32_dpp v178, v4, v204 row_shl:1 row_mask:0xf bank_mask:0xf bound_ctrl:1
	v_fmac_f32_dpp v179, v5, v205 row_shl:1 row_mask:0xf bank_mask:0xf bound_ctrl:1
	v_fmac_f32_dpp v208, v6, v206 row_shl:1 row_mask:0xf bank_mask:0xf bound_ctrl:1
	v_fmac_f32_dpp v209, v7, v207 row_shl:1 row_mask:0xf bank_mask:0xf bound_ctrl:1
	v_pk_mul_f32 v[180:181], v[188:189], s[100:101] op_sel_hi:[1,0]
	v_pk_mul_f32 v[182:183], v[190:191], s[100:101] op_sel_hi:[1,0]
	v_pk_mul_f32 v[184:185], v[178:179], s[100:101] op_sel_hi:[1,0]
	v_pk_mul_f32 v[186:187], v[208:209], s[100:101] op_sel_hi:[1,0]
	v_exp_f32_e32 v180, v180
	v_exp_f32_e32 v181, v181
	v_exp_f32_e32 v182, v182
	v_exp_f32_e32 v183, v183
	v_exp_f32_e32 v184, v184
	v_exp_f32_e32 v185, v185
	v_exp_f32_e32 v186, v186
	v_exp_f32_e32 v187, v187
	v_pk_add_f32 v[180:181], v[180:181], 1.0 op_sel_hi:[1,0]
	v_pk_add_f32 v[182:183], v[182:183], 1.0 op_sel_hi:[1,0]
	v_pk_add_f32 v[184:185], v[184:185], 1.0 op_sel_hi:[1,0]
	v_pk_add_f32 v[186:187], v[186:187], 1.0 op_sel_hi:[1,0]
	v_rcp_f32_e32 v180, v180
	v_rcp_f32_e32 v181, v181
	v_rcp_f32_e32 v182, v182
	v_rcp_f32_e32 v183, v183
	v_rcp_f32_e32 v184, v184
	v_rcp_f32_e32 v185, v185
	v_rcp_f32_e32 v186, v186
	v_rcp_f32_e32 v187, v187
	v_pk_mul_f32 v[188:189], v[188:189], v[180:181]
	v_pk_mul_f32 v[190:191], v[190:191], v[182:183]
	v_pk_mul_f32 v[178:179], v[178:179], v[184:185]
	v_pk_mul_f32 v[208:209], v[208:209], v[186:187]
	v_pk_mul_f32 v[180:181], v[52:53], v[132:133]
	v_pk_mul_f32 v[182:183], v[54:55], v[134:135]
	v_pk_mul_f32 v[184:185], v[36:37], v[234:235]
	v_pk_mul_f32 v[186:187], v[38:39], v[236:237]
	v_pk_fma_f32 v[180:181], v[40:41], v[136:137], v[180:181]
	v_pk_fma_f32 v[182:183], v[42:43], v[138:139], v[182:183]
	v_pk_fma_f32 v[184:185], v[28:29], v[238:239], v[184:185]
	v_pk_fma_f32 v[186:187], v[30:31], v[240:241], v[186:187]
	v_fmac_f32_dpp v180, v64, v140 row_shl:1 row_mask:0xf bank_mask:0xf bound_ctrl:1
	v_fmac_f32_dpp v181, v65, v141 row_shl:1 row_mask:0xf bank_mask:0xf bound_ctrl:1
	v_fmac_f32_dpp v182, v66, v142 row_shl:1 row_mask:0xf bank_mask:0xf bound_ctrl:1
	v_fmac_f32_dpp v183, v67, v143 row_shl:1 row_mask:0xf bank_mask:0xf bound_ctrl:1
	v_fmac_f32_dpp v184, v56, v242 row_shl:1 row_mask:0xf bank_mask:0xf bound_ctrl:1
	v_fmac_f32_dpp v185, v57, v243 row_shl:1 row_mask:0xf bank_mask:0xf bound_ctrl:1
	v_fmac_f32_dpp v186, v58, v244 row_shl:1 row_mask:0xf bank_mask:0xf bound_ctrl:1
	v_fmac_f32_dpp v187, v59, v245 row_shl:1 row_mask:0xf bank_mask:0xf bound_ctrl:1
	v_pk_mul_f32 v[180:181], v[180:181], v[188:189]
	v_pk_mul_f32 v[182:183], v[182:183], v[190:191]
	v_pk_mul_f32 v[184:185], v[184:185], v[178:179]
	v_pk_mul_f32 v[186:187], v[186:187], v[208:209]
	v_cvt_pk_bf16_f32 v216, v180, v181
	v_cvt_pk_bf16_f32 v217, v182, v183
	v_cvt_pk_bf16_f32 v218, v184, v185
	v_cvt_pk_bf16_f32 v219, v186, v187
	global_store_dwordx4 v[214:215], v[216:219], off
	s_mov_b32 s4, 0xffff7c00
	s_mov_b32 s5, -1
	v_lshl_add_u64 v[214:215], v[214:215], 0, s[4:5]
	v_pk_mul_f32 v[188:189], v[48:49], v[144:145]
	v_pk_mul_f32 v[190:191], v[50:51], v[146:147]
	v_pk_mul_f32 v[178:179], v[4:5], v[246:247]
	v_pk_mul_f32 v[208:209], v[6:7], v[248:249]
	v_pk_fma_f32 v[188:189], v[44:45], v[148:149], v[188:189]
	v_pk_fma_f32 v[190:191], v[46:47], v[150:151], v[190:191]
	v_pk_fma_f32 v[178:179], v[8:9], v[200:201], v[178:179]
	v_pk_fma_f32 v[208:209], v[10:11], v[202:203], v[208:209]
	v_pk_fma_f32 v[188:189], v[120:121], v[152:153], v[188:189]
	v_pk_fma_f32 v[190:191], v[122:123], v[154:155], v[190:191]
	v_pk_fma_f32 v[178:179], v[88:89], v[204:205], v[178:179]
	v_pk_fma_f32 v[208:209], v[90:91], v[206:207], v[208:209]
	v_pk_mul_f32 v[180:181], v[188:189], s[100:101] op_sel_hi:[1,0]
	v_pk_mul_f32 v[182:183], v[190:191], s[100:101] op_sel_hi:[1,0]
	v_pk_mul_f32 v[184:185], v[178:179], s[100:101] op_sel_hi:[1,0]
	v_pk_mul_f32 v[186:187], v[208:209], s[100:101] op_sel_hi:[1,0]
	v_exp_f32_e32 v180, v180
	v_exp_f32_e32 v181, v181
	v_exp_f32_e32 v182, v182
	v_exp_f32_e32 v183, v183
	v_exp_f32_e32 v184, v184
	v_exp_f32_e32 v185, v185
	v_exp_f32_e32 v186, v186
	v_exp_f32_e32 v187, v187
	v_pk_add_f32 v[180:181], v[180:181], 1.0 op_sel_hi:[1,0]
	v_pk_add_f32 v[182:183], v[182:183], 1.0 op_sel_hi:[1,0]
	v_pk_add_f32 v[184:185], v[184:185], 1.0 op_sel_hi:[1,0]
	v_pk_add_f32 v[186:187], v[186:187], 1.0 op_sel_hi:[1,0]
	v_rcp_f32_e32 v180, v180
	v_rcp_f32_e32 v181, v181
	v_rcp_f32_e32 v182, v182
	v_rcp_f32_e32 v183, v183
	v_rcp_f32_e32 v184, v184
	v_rcp_f32_e32 v185, v185
	v_rcp_f32_e32 v186, v186
	v_rcp_f32_e32 v187, v187
	v_pk_mul_f32 v[188:189], v[188:189], v[180:181]
	v_pk_mul_f32 v[190:191], v[190:191], v[182:183]
	v_pk_mul_f32 v[178:179], v[178:179], v[184:185]
	v_pk_mul_f32 v[208:209], v[208:209], v[186:187]
	v_pk_mul_f32 v[180:181], v[64:65], v[132:133]
	v_pk_mul_f32 v[182:183], v[66:67], v[134:135]
	v_pk_mul_f32 v[184:185], v[56:57], v[234:235]
	v_pk_mul_f32 v[186:187], v[58:59], v[236:237]
	v_pk_fma_f32 v[180:181], v[60:61], v[136:137], v[180:181]
	v_pk_fma_f32 v[182:183], v[62:63], v[138:139], v[182:183]
	v_pk_fma_f32 v[184:185], v[20:21], v[238:239], v[184:185]
	v_pk_fma_f32 v[186:187], v[22:23], v[240:241], v[186:187]
	v_pk_fma_f32 v[180:181], v[128:129], v[140:141], v[180:181]
	v_pk_fma_f32 v[182:183], v[130:131], v[142:143], v[182:183]
	v_pk_fma_f32 v[184:185], v[96:97], v[242:243], v[184:185]
	v_pk_fma_f32 v[186:187], v[98:99], v[244:245], v[186:187]
	v_pk_mul_f32 v[180:181], v[180:181], v[188:189]
	v_pk_mul_f32 v[182:183], v[182:183], v[190:191]
	v_pk_mul_f32 v[184:185], v[184:185], v[178:179]
	v_pk_mul_f32 v[186:187], v[186:187], v[208:209]
	v_cvt_pk_bf16_f32 v216, v180, v181
	v_cvt_pk_bf16_f32 v217, v182, v183
	v_cvt_pk_bf16_f32 v218, v184, v185
	v_cvt_pk_bf16_f32 v219, v186, v187
	global_store_dwordx4 v[214:215], v[216:219], off
	s_mov_b32 s4, 0x1600
	s_mov_b32 s5, 0
	v_lshl_add_u64 v[214:215], v[214:215], 0, s[4:5]
	v_pk_mul_f32 v[188:189], v[44:45], v[144:145]
	v_pk_mul_f32 v[190:191], v[46:47], v[146:147]
	v_pk_mul_f32 v[178:179], v[8:9], v[246:247]
	v_pk_mul_f32 v[208:209], v[10:11], v[248:249]
	v_pk_fma_f32 v[188:189], v[120:121], v[148:149], v[188:189]
	v_pk_fma_f32 v[190:191], v[122:123], v[150:151], v[190:191]
	v_pk_fma_f32 v[178:179], v[88:89], v[200:201], v[178:179]
	v_pk_fma_f32 v[208:209], v[90:91], v[202:203], v[208:209]
	v_pk_fma_f32 v[188:189], v[112:113], v[152:153], v[188:189]
	v_pk_fma_f32 v[190:191], v[114:115], v[154:155], v[190:191]
	v_pk_fma_f32 v[178:179], v[80:81], v[204:205], v[178:179]
	v_pk_fma_f32 v[208:209], v[82:83], v[206:207], v[208:209]
	v_pk_mul_f32 v[180:181], v[188:189], s[100:101] op_sel_hi:[1,0]
	v_pk_mul_f32 v[182:183], v[190:191], s[100:101] op_sel_hi:[1,0]
	v_pk_mul_f32 v[184:185], v[178:179], s[100:101] op_sel_hi:[1,0]
	v_pk_mul_f32 v[186:187], v[208:209], s[100:101] op_sel_hi:[1,0]
	v_exp_f32_e32 v180, v180
	v_exp_f32_e32 v181, v181
	v_exp_f32_e32 v182, v182
	v_exp_f32_e32 v183, v183
	v_exp_f32_e32 v184, v184
	v_exp_f32_e32 v185, v185
	v_exp_f32_e32 v186, v186
	v_exp_f32_e32 v187, v187
	v_pk_add_f32 v[180:181], v[180:181], 1.0 op_sel_hi:[1,0]
	v_pk_add_f32 v[182:183], v[182:183], 1.0 op_sel_hi:[1,0]
	v_pk_add_f32 v[184:185], v[184:185], 1.0 op_sel_hi:[1,0]
	v_pk_add_f32 v[186:187], v[186:187], 1.0 op_sel_hi:[1,0]
	v_rcp_f32_e32 v180, v180
	v_rcp_f32_e32 v181, v181
	v_rcp_f32_e32 v182, v182
	v_rcp_f32_e32 v183, v183
	v_rcp_f32_e32 v184, v184
	v_rcp_f32_e32 v185, v185
	v_rcp_f32_e32 v186, v186
	v_rcp_f32_e32 v187, v187
	v_pk_mul_f32 v[188:189], v[188:189], v[180:181]
	v_pk_mul_f32 v[190:191], v[190:191], v[182:183]
	v_pk_mul_f32 v[178:179], v[178:179], v[184:185]
	v_pk_mul_f32 v[208:209], v[208:209], v[186:187]
	v_pk_mul_f32 v[180:181], v[60:61], v[132:133]
	v_pk_mul_f32 v[182:183], v[62:63], v[134:135]
	v_pk_mul_f32 v[184:185], v[20:21], v[234:235]
	v_pk_mul_f32 v[186:187], v[22:23], v[236:237]
	v_pk_fma_f32 v[180:181], v[128:129], v[136:137], v[180:181]
	v_pk_fma_f32 v[182:183], v[130:131], v[138:139], v[182:183]
	v_pk_fma_f32 v[184:185], v[96:97], v[238:239], v[184:185]
	v_pk_fma_f32 v[186:187], v[98:99], v[240:241], v[186:187]
	v_pk_fma_f32 v[180:181], v[124:125], v[140:141], v[180:181]
	v_pk_fma_f32 v[182:183], v[126:127], v[142:143], v[182:183]
	v_pk_fma_f32 v[184:185], v[92:93], v[242:243], v[184:185]
	v_pk_fma_f32 v[186:187], v[94:95], v[244:245], v[186:187]
	v_pk_mul_f32 v[180:181], v[180:181], v[188:189]
	v_pk_mul_f32 v[182:183], v[182:183], v[190:191]
	v_pk_mul_f32 v[184:185], v[184:185], v[178:179]
	v_pk_mul_f32 v[186:187], v[186:187], v[208:209]
	v_cvt_pk_bf16_f32 v216, v180, v181
	v_cvt_pk_bf16_f32 v217, v182, v183
	v_cvt_pk_bf16_f32 v218, v184, v185
	v_cvt_pk_bf16_f32 v219, v186, v187
	global_store_dwordx4 v[214:215], v[216:219], off
	s_mov_b32 s4, 0x1600
	s_mov_b32 s5, 0
	v_lshl_add_u64 v[214:215], v[214:215], 0, s[4:5]
	v_pk_mul_f32 v[188:189], v[120:121], v[144:145]
	v_pk_mul_f32 v[190:191], v[122:123], v[146:147]
	v_pk_mul_f32 v[178:179], v[88:89], v[246:247]
	v_pk_mul_f32 v[208:209], v[90:91], v[248:249]
	v_pk_fma_f32 v[188:189], v[112:113], v[148:149], v[188:189]
	v_pk_fma_f32 v[190:191], v[114:115], v[150:151], v[190:191]
	v_pk_fma_f32 v[178:179], v[80:81], v[200:201], v[178:179]
	v_pk_fma_f32 v[208:209], v[82:83], v[202:203], v[208:209]
	v_pk_fma_f32 v[188:189], v[104:105], v[152:153], v[188:189]
	v_pk_fma_f32 v[190:191], v[106:107], v[154:155], v[190:191]
	v_pk_fma_f32 v[178:179], v[72:73], v[204:205], v[178:179]
	v_pk_fma_f32 v[208:209], v[74:75], v[206:207], v[208:209]
	v_pk_mul_f32 v[180:181], v[188:189], s[100:101] op_sel_hi:[1,0]
	v_pk_mul_f32 v[182:183], v[190:191], s[100:101] op_sel_hi:[1,0]
	v_pk_mul_f32 v[184:185], v[178:179], s[100:101] op_sel_hi:[1,0]
	v_pk_mul_f32 v[186:187], v[208:209], s[100:101] op_sel_hi:[1,0]
	v_exp_f32_e32 v180, v180
	v_exp_f32_e32 v181, v181
	v_exp_f32_e32 v182, v182
	v_exp_f32_e32 v183, v183
	v_exp_f32_e32 v184, v184
	v_exp_f32_e32 v185, v185
	v_exp_f32_e32 v186, v186
	v_exp_f32_e32 v187, v187
	v_pk_add_f32 v[180:181], v[180:181], 1.0 op_sel_hi:[1,0]
	v_pk_add_f32 v[182:183], v[182:183], 1.0 op_sel_hi:[1,0]
	v_pk_add_f32 v[184:185], v[184:185], 1.0 op_sel_hi:[1,0]
	v_pk_add_f32 v[186:187], v[186:187], 1.0 op_sel_hi:[1,0]
	v_rcp_f32_e32 v180, v180
	v_rcp_f32_e32 v181, v181
	v_rcp_f32_e32 v182, v182
	v_rcp_f32_e32 v183, v183
	v_rcp_f32_e32 v184, v184
	v_rcp_f32_e32 v185, v185
	v_rcp_f32_e32 v186, v186
	v_rcp_f32_e32 v187, v187
	v_pk_mul_f32 v[188:189], v[188:189], v[180:181]
	v_pk_mul_f32 v[190:191], v[190:191], v[182:183]
	v_pk_mul_f32 v[178:179], v[178:179], v[184:185]
	v_pk_mul_f32 v[208:209], v[208:209], v[186:187]
	v_pk_mul_f32 v[180:181], v[128:129], v[132:133]
	v_pk_mul_f32 v[182:183], v[130:131], v[134:135]
	v_pk_mul_f32 v[184:185], v[96:97], v[234:235]
	v_pk_mul_f32 v[186:187], v[98:99], v[236:237]
	v_pk_fma_f32 v[180:181], v[124:125], v[136:137], v[180:181]
	v_pk_fma_f32 v[182:183], v[126:127], v[138:139], v[182:183]
	v_pk_fma_f32 v[184:185], v[92:93], v[238:239], v[184:185]
	v_pk_fma_f32 v[186:187], v[94:95], v[240:241], v[186:187]
	v_pk_fma_f32 v[180:181], v[116:117], v[140:141], v[180:181]
	v_pk_fma_f32 v[182:183], v[118:119], v[142:143], v[182:183]
	v_pk_fma_f32 v[184:185], v[84:85], v[242:243], v[184:185]
	v_pk_fma_f32 v[186:187], v[86:87], v[244:245], v[186:187]
	v_pk_mul_f32 v[180:181], v[180:181], v[188:189]
	v_pk_mul_f32 v[182:183], v[182:183], v[190:191]
	v_pk_mul_f32 v[184:185], v[184:185], v[178:179]
	v_pk_mul_f32 v[186:187], v[186:187], v[208:209]
	v_cvt_pk_bf16_f32 v216, v180, v181
	v_cvt_pk_bf16_f32 v217, v182, v183
	v_cvt_pk_bf16_f32 v218, v184, v185
	v_cvt_pk_bf16_f32 v219, v186, v187
	global_store_dwordx4 v[214:215], v[216:219], off
	s_mov_b32 s4, 0x1600
	s_mov_b32 s5, 0
	v_lshl_add_u64 v[214:215], v[214:215], 0, s[4:5]
	v_pk_mul_f32 v[188:189], v[112:113], v[144:145]
	v_pk_mul_f32 v[190:191], v[114:115], v[146:147]
	v_pk_mul_f32 v[178:179], v[80:81], v[246:247]
	v_pk_mul_f32 v[208:209], v[82:83], v[248:249]
	v_pk_fma_f32 v[188:189], v[104:105], v[148:149], v[188:189]
	v_pk_fma_f32 v[190:191], v[106:107], v[150:151], v[190:191]
	v_pk_fma_f32 v[178:179], v[72:73], v[200:201], v[178:179]
	v_pk_fma_f32 v[208:209], v[74:75], v[202:203], v[208:209]
	v_pk_fma_f32 v[188:189], v[100:101], v[152:153], v[188:189]
	v_pk_fma_f32 v[190:191], v[102:103], v[154:155], v[190:191]
	v_pk_fma_f32 v[178:179], v[68:69], v[204:205], v[178:179]
	v_pk_fma_f32 v[208:209], v[70:71], v[206:207], v[208:209]
	v_pk_mul_f32 v[180:181], v[188:189], s[100:101] op_sel_hi:[1,0]
	v_pk_mul_f32 v[182:183], v[190:191], s[100:101] op_sel_hi:[1,0]
	v_pk_mul_f32 v[184:185], v[178:179], s[100:101] op_sel_hi:[1,0]
	v_pk_mul_f32 v[186:187], v[208:209], s[100:101] op_sel_hi:[1,0]
	v_exp_f32_e32 v180, v180
	v_exp_f32_e32 v181, v181
	v_exp_f32_e32 v182, v182
	v_exp_f32_e32 v183, v183
	v_exp_f32_e32 v184, v184
	v_exp_f32_e32 v185, v185
	v_exp_f32_e32 v186, v186
	v_exp_f32_e32 v187, v187
	v_pk_add_f32 v[180:181], v[180:181], 1.0 op_sel_hi:[1,0]
	v_pk_add_f32 v[182:183], v[182:183], 1.0 op_sel_hi:[1,0]
	v_pk_add_f32 v[184:185], v[184:185], 1.0 op_sel_hi:[1,0]
	v_pk_add_f32 v[186:187], v[186:187], 1.0 op_sel_hi:[1,0]
	v_rcp_f32_e32 v180, v180
	v_rcp_f32_e32 v181, v181
	v_rcp_f32_e32 v182, v182
	v_rcp_f32_e32 v183, v183
	v_rcp_f32_e32 v184, v184
	v_rcp_f32_e32 v185, v185
	v_rcp_f32_e32 v186, v186
	v_rcp_f32_e32 v187, v187
	v_pk_mul_f32 v[188:189], v[188:189], v[180:181]
	v_pk_mul_f32 v[190:191], v[190:191], v[182:183]
	v_pk_mul_f32 v[178:179], v[178:179], v[184:185]
	v_pk_mul_f32 v[208:209], v[208:209], v[186:187]
	v_pk_mul_f32 v[180:181], v[124:125], v[132:133]
	v_pk_mul_f32 v[182:183], v[126:127], v[134:135]
	v_pk_mul_f32 v[184:185], v[92:93], v[234:235]
	v_pk_mul_f32 v[186:187], v[94:95], v[236:237]
	v_pk_fma_f32 v[180:181], v[116:117], v[136:137], v[180:181]
	v_pk_fma_f32 v[182:183], v[118:119], v[138:139], v[182:183]
	v_pk_fma_f32 v[184:185], v[84:85], v[238:239], v[184:185]
	v_pk_fma_f32 v[186:187], v[86:87], v[240:241], v[186:187]
	v_pk_fma_f32 v[180:181], v[108:109], v[140:141], v[180:181]
	v_pk_fma_f32 v[182:183], v[110:111], v[142:143], v[182:183]
	v_pk_fma_f32 v[184:185], v[76:77], v[242:243], v[184:185]
	v_pk_fma_f32 v[186:187], v[78:79], v[244:245], v[186:187]
	v_pk_mul_f32 v[180:181], v[180:181], v[188:189]
	v_pk_mul_f32 v[182:183], v[182:183], v[190:191]
	v_pk_mul_f32 v[184:185], v[184:185], v[178:179]
	v_pk_mul_f32 v[186:187], v[186:187], v[208:209]
	v_cvt_pk_bf16_f32 v216, v180, v181
	v_cvt_pk_bf16_f32 v217, v182, v183
	v_cvt_pk_bf16_f32 v218, v184, v185
	v_cvt_pk_bf16_f32 v219, v186, v187
	global_store_dwordx4 v[214:215], v[216:219], off
	s_mov_b32 s4, 0x1600
	s_mov_b32 s5, 0
	v_lshl_add_u64 v[214:215], v[214:215], 0, s[4:5]
	v_pk_mul_f32 v[188:189], v[104:105], v[144:145]
	v_pk_mul_f32 v[190:191], v[106:107], v[146:147]
	v_pk_mul_f32 v[178:179], v[72:73], v[246:247]
	v_pk_mul_f32 v[208:209], v[74:75], v[248:249]
	v_pk_fma_f32 v[188:189], v[100:101], v[148:149], v[188:189]
	v_pk_fma_f32 v[190:191], v[102:103], v[150:151], v[190:191]
	v_pk_fma_f32 v[178:179], v[68:69], v[200:201], v[178:179]
	v_pk_fma_f32 v[208:209], v[70:71], v[202:203], v[208:209]
	v_pk_fma_f32 v[188:189], v[32:33], v[152:153], v[188:189]
	v_pk_fma_f32 v[190:191], v[34:35], v[154:155], v[190:191]
	v_pk_fma_f32 v[178:179], v[12:13], v[204:205], v[178:179]
	v_pk_fma_f32 v[208:209], v[14:15], v[206:207], v[208:209]
	v_pk_mul_f32 v[180:181], v[188:189], s[100:101] op_sel_hi:[1,0]
	v_pk_mul_f32 v[182:183], v[190:191], s[100:101] op_sel_hi:[1,0]
	v_pk_mul_f32 v[184:185], v[178:179], s[100:101] op_sel_hi:[1,0]
	v_pk_mul_f32 v[186:187], v[208:209], s[100:101] op_sel_hi:[1,0]
	v_exp_f32_e32 v180, v180
	v_exp_f32_e32 v181, v181
	v_exp_f32_e32 v182, v182
	v_exp_f32_e32 v183, v183
	v_exp_f32_e32 v184, v184
	v_exp_f32_e32 v185, v185
	v_exp_f32_e32 v186, v186
	v_exp_f32_e32 v187, v187
	v_pk_add_f32 v[180:181], v[180:181], 1.0 op_sel_hi:[1,0]
	v_pk_add_f32 v[182:183], v[182:183], 1.0 op_sel_hi:[1,0]
	v_pk_add_f32 v[184:185], v[184:185], 1.0 op_sel_hi:[1,0]
	v_pk_add_f32 v[186:187], v[186:187], 1.0 op_sel_hi:[1,0]
	v_rcp_f32_e32 v180, v180
	v_rcp_f32_e32 v181, v181
	v_rcp_f32_e32 v182, v182
	v_rcp_f32_e32 v183, v183
	v_rcp_f32_e32 v184, v184
	v_rcp_f32_e32 v185, v185
	v_rcp_f32_e32 v186, v186
	v_rcp_f32_e32 v187, v187
	v_pk_mul_f32 v[188:189], v[188:189], v[180:181]
	v_pk_mul_f32 v[190:191], v[190:191], v[182:183]
	v_pk_mul_f32 v[178:179], v[178:179], v[184:185]
	v_pk_mul_f32 v[208:209], v[208:209], v[186:187]
	v_pk_mul_f32 v[180:181], v[116:117], v[132:133]
	v_pk_mul_f32 v[182:183], v[118:119], v[134:135]
	v_pk_mul_f32 v[184:185], v[84:85], v[234:235]
	v_pk_mul_f32 v[186:187], v[86:87], v[236:237]
	v_pk_fma_f32 v[180:181], v[108:109], v[136:137], v[180:181]
	v_pk_fma_f32 v[182:183], v[110:111], v[138:139], v[182:183]
	v_pk_fma_f32 v[184:185], v[76:77], v[238:239], v[184:185]
	v_pk_fma_f32 v[186:187], v[78:79], v[240:241], v[186:187]
	v_pk_fma_f32 v[180:181], v[52:53], v[140:141], v[180:181]
	v_pk_fma_f32 v[182:183], v[54:55], v[142:143], v[182:183]
	v_pk_fma_f32 v[184:185], v[36:37], v[242:243], v[184:185]
	v_pk_fma_f32 v[186:187], v[38:39], v[244:245], v[186:187]
	v_pk_mul_f32 v[180:181], v[180:181], v[188:189]
	v_pk_mul_f32 v[182:183], v[182:183], v[190:191]
	v_pk_mul_f32 v[184:185], v[184:185], v[178:179]
	v_pk_mul_f32 v[186:187], v[186:187], v[208:209]
	v_cvt_pk_bf16_f32 v216, v180, v181
	v_cvt_pk_bf16_f32 v217, v182, v183
	v_cvt_pk_bf16_f32 v218, v184, v185
	v_cvt_pk_bf16_f32 v219, v186, v187
	global_store_dwordx4 v[214:215], v[216:219], off
	s_mov_b32 s4, 0x1600
	s_mov_b32 s5, 0
	v_lshl_add_u64 v[214:215], v[214:215], 0, s[4:5]
	v_pk_mul_f32 v[188:189], v[100:101], v[144:145]
	v_pk_mul_f32 v[190:191], v[102:103], v[146:147]
	v_pk_mul_f32 v[178:179], v[68:69], v[246:247]
	v_pk_mul_f32 v[208:209], v[70:71], v[248:249]
	v_pk_fma_f32 v[188:189], v[32:33], v[148:149], v[188:189]
	v_pk_fma_f32 v[190:191], v[34:35], v[150:151], v[190:191]
	v_pk_fma_f32 v[178:179], v[12:13], v[200:201], v[178:179]
	v_pk_fma_f32 v[208:209], v[14:15], v[202:203], v[208:209]
	v_pk_fma_f32 v[188:189], v[24:25], v[152:153], v[188:189]
	v_pk_fma_f32 v[190:191], v[26:27], v[154:155], v[190:191]
	v_pk_fma_f32 v[178:179], v[16:17], v[204:205], v[178:179]
	v_pk_fma_f32 v[208:209], v[18:19], v[206:207], v[208:209]
	v_pk_mul_f32 v[180:181], v[188:189], s[100:101] op_sel_hi:[1,0]
	v_pk_mul_f32 v[182:183], v[190:191], s[100:101] op_sel_hi:[1,0]
	v_pk_mul_f32 v[184:185], v[178:179], s[100:101] op_sel_hi:[1,0]
	v_pk_mul_f32 v[186:187], v[208:209], s[100:101] op_sel_hi:[1,0]
	v_exp_f32_e32 v180, v180
	v_exp_f32_e32 v181, v181
	v_exp_f32_e32 v182, v182
	v_exp_f32_e32 v183, v183
	v_exp_f32_e32 v184, v184
	v_exp_f32_e32 v185, v185
	v_exp_f32_e32 v186, v186
	v_exp_f32_e32 v187, v187
	v_pk_add_f32 v[180:181], v[180:181], 1.0 op_sel_hi:[1,0]
	v_pk_add_f32 v[182:183], v[182:183], 1.0 op_sel_hi:[1,0]
	v_pk_add_f32 v[184:185], v[184:185], 1.0 op_sel_hi:[1,0]
	v_pk_add_f32 v[186:187], v[186:187], 1.0 op_sel_hi:[1,0]
	v_rcp_f32_e32 v180, v180
	v_rcp_f32_e32 v181, v181
	v_rcp_f32_e32 v182, v182
	v_rcp_f32_e32 v183, v183
	v_rcp_f32_e32 v184, v184
	v_rcp_f32_e32 v185, v185
	v_rcp_f32_e32 v186, v186
	v_rcp_f32_e32 v187, v187
	v_pk_mul_f32 v[188:189], v[188:189], v[180:181]
	v_pk_mul_f32 v[190:191], v[190:191], v[182:183]
	v_pk_mul_f32 v[178:179], v[178:179], v[184:185]
	v_pk_mul_f32 v[208:209], v[208:209], v[186:187]
	v_pk_mul_f32 v[180:181], v[108:109], v[132:133]
	v_pk_mul_f32 v[182:183], v[110:111], v[134:135]
	v_pk_mul_f32 v[184:185], v[76:77], v[234:235]
	v_pk_mul_f32 v[186:187], v[78:79], v[236:237]
	v_pk_fma_f32 v[180:181], v[52:53], v[136:137], v[180:181]
	v_pk_fma_f32 v[182:183], v[54:55], v[138:139], v[182:183]
	v_pk_fma_f32 v[184:185], v[36:37], v[238:239], v[184:185]
	v_pk_fma_f32 v[186:187], v[38:39], v[240:241], v[186:187]
	v_pk_fma_f32 v[180:181], v[40:41], v[140:141], v[180:181]
	v_pk_fma_f32 v[182:183], v[42:43], v[142:143], v[182:183]
	v_pk_fma_f32 v[184:185], v[28:29], v[242:243], v[184:185]
	v_pk_fma_f32 v[186:187], v[30:31], v[244:245], v[186:187]
	v_pk_mul_f32 v[180:181], v[180:181], v[188:189]
	v_pk_mul_f32 v[182:183], v[182:183], v[190:191]
	v_pk_mul_f32 v[184:185], v[184:185], v[178:179]
	v_pk_mul_f32 v[186:187], v[186:187], v[208:209]
	v_cvt_pk_bf16_f32 v216, v180, v181
	v_cvt_pk_bf16_f32 v217, v182, v183
	v_cvt_pk_bf16_f32 v218, v184, v185
	v_cvt_pk_bf16_f32 v219, v186, v187
	global_store_dwordx4 v[214:215], v[216:219], off
	s_andn2_b64 vcc, exec, s[12:13]
	s_mov_b64 s[12:13], -1
	s_cbranch_vccnz .LBB0_1235
